# route layer-1 final product-key merge rewritten like layer 0 (16 parallel LDS reads + compare/select tree per round)
# baseline (speedup 1.0000x reference)
.LBB0_1087:
	s_and_saveexec_b64 s[8:9], s[6:7]
	s_cbranch_execz .LBB0_1081
	v_or_b32_e32 v254, s56, v156
	v_lshlrev_b32_e32 v254, 9, v254
	v_lshl_or_b32 v254, s55, 6, v254
	ds_read_b32 v32, v105 offset:0
	ds_read_b32 v33, v105 offset:512
	ds_read_b32 v34, v105 offset:1024
	ds_read_b32 v35, v105 offset:1536
	ds_read_b32 v36, v105 offset:2048
	ds_read_b32 v37, v105 offset:2560
	ds_read_b32 v38, v105 offset:3072
	ds_read_b32 v39, v105 offset:3584
	ds_read_b32 v40, v105 offset:4096
	ds_read_b32 v41, v105 offset:4608
	ds_read_b32 v42, v105 offset:5120
	ds_read_b32 v43, v105 offset:5632
	ds_read_b32 v44, v105 offset:6144
	ds_read_b32 v45, v105 offset:6656
	ds_read_b32 v46, v105 offset:7168
	ds_read_b32 v47, v105 offset:7680
	v_mov_b32_e32 v48, 0
	v_mov_b32_e32 v49, 0
	v_bfe_u32 v0, v48, 0, 4
	v_bfe_u32 v1, v48, 4, 4
	v_bfe_u32 v2, v48, 8, 4
	v_bfe_u32 v3, v48, 12, 4
	v_bfe_u32 v4, v48, 16, 4
	v_bfe_u32 v5, v48, 20, 4
	v_bfe_u32 v6, v48, 24, 4
	v_bfe_u32 v7, v48, 28, 4
	v_bfe_u32 v8, v49, 0, 4
	v_bfe_u32 v9, v49, 4, 4
	v_bfe_u32 v10, v49, 8, 4
	v_bfe_u32 v11, v49, 12, 4
	v_bfe_u32 v12, v49, 16, 4
	v_bfe_u32 v13, v49, 20, 4
	v_bfe_u32 v14, v49, 24, 4
	v_bfe_u32 v15, v49, 28, 4
	v_lshl_add_u32 v0, v0, 9, v106
	v_lshl_add_u32 v1, v1, 9, v106
	v_lshl_add_u32 v2, v2, 9, v106
	v_lshl_add_u32 v3, v3, 9, v106
	v_lshl_add_u32 v4, v4, 9, v106
	v_lshl_add_u32 v5, v5, 9, v106
	v_lshl_add_u32 v6, v6, 9, v106
	v_lshl_add_u32 v7, v7, 9, v106
	v_lshl_add_u32 v8, v8, 9, v106
	v_lshl_add_u32 v9, v9, 9, v106
	v_lshl_add_u32 v10, v10, 9, v106
	v_lshl_add_u32 v11, v11, 9, v106
	v_lshl_add_u32 v12, v12, 9, v106
	v_lshl_add_u32 v13, v13, 9, v106
	v_lshl_add_u32 v14, v14, 9, v106
	v_lshl_add_u32 v15, v15, 9, v106
	ds_read_b32 v0, v0 offset:32768
	ds_read_b32 v1, v1 offset:32768
	ds_read_b32 v2, v2 offset:32768
	ds_read_b32 v3, v3 offset:32768
	ds_read_b32 v4, v4 offset:32768
	ds_read_b32 v5, v5 offset:32768
	ds_read_b32 v6, v6 offset:32768
	ds_read_b32 v7, v7 offset:32768
	ds_read_b32 v8, v8 offset:32768
	ds_read_b32 v9, v9 offset:32768
	ds_read_b32 v10, v10 offset:32768
	ds_read_b32 v11, v11 offset:32768
	ds_read_b32 v12, v12 offset:32768
	ds_read_b32 v13, v13 offset:32768
	ds_read_b32 v14, v14 offset:32768
	ds_read_b32 v15, v15 offset:32768
	s_waitcnt lgkmcnt(0)
	v_add_f32_e32 v0, v32, v0
	v_add_f32_e32 v1, v33, v1
	v_add_f32_e32 v2, v34, v2
	v_add_f32_e32 v3, v35, v3
	v_add_f32_e32 v4, v36, v4
	v_add_f32_e32 v5, v37, v5
	v_add_f32_e32 v6, v38, v6
	v_add_f32_e32 v7, v39, v7
	v_add_f32_e32 v8, v40, v8
	v_add_f32_e32 v9, v41, v9
	v_add_f32_e32 v10, v42, v10
	v_add_f32_e32 v11, v43, v11
	v_add_f32_e32 v12, v44, v12
	v_add_f32_e32 v13, v45, v13
	v_add_f32_e32 v14, v46, v14
	v_add_f32_e32 v15, v47, v15
	v_cmp_gt_f32_e32 vcc, v1, v0
	v_cmp_gt_f32_e64 s[18:19], v3, v2
	v_cmp_gt_f32_e64 s[98:99], v5, v4
	v_cmp_gt_f32_e64 s[100:101], v7, v6
	v_cndmask_b32_e64 v0, v0, v1, vcc
	v_cndmask_b32_e64 v1, 0, 1, vcc
	v_cndmask_b32_e64 v2, v2, v3, s[18:19]
	v_cndmask_b32_e64 v3, 2, 3, s[18:19]
	v_cndmask_b32_e64 v4, v4, v5, s[98:99]
	v_cndmask_b32_e64 v5, 4, 5, s[98:99]
	v_cndmask_b32_e64 v6, v6, v7, s[100:101]
	v_cndmask_b32_e64 v7, 6, 7, s[100:101]
	v_cmp_gt_f32_e32 vcc, v9, v8
	v_cmp_gt_f32_e64 s[18:19], v11, v10
	v_cmp_gt_f32_e64 s[98:99], v13, v12
	v_cmp_gt_f32_e64 s[100:101], v15, v14
	v_cndmask_b32_e64 v8, v8, v9, vcc
	v_cndmask_b32_e64 v9, 8, 9, vcc
	v_cndmask_b32_e64 v10, v10, v11, s[18:19]
	v_cndmask_b32_e64 v11, 10, 11, s[18:19]
	v_cndmask_b32_e64 v12, v12, v13, s[98:99]
	v_cndmask_b32_e64 v13, 12, 13, s[98:99]
	v_cndmask_b32_e64 v14, v14, v15, s[100:101]
	v_cndmask_b32_e64 v15, 14, 15, s[100:101]
	v_cmp_gt_f32_e32 vcc, v2, v0
	v_cmp_gt_f32_e64 s[18:19], v6, v4
	v_cmp_gt_f32_e64 s[98:99], v10, v8
	v_cmp_gt_f32_e64 s[100:101], v14, v12
	v_cndmask_b32_e64 v0, v0, v2, vcc
	v_cndmask_b32_e64 v1, v1, v3, vcc
	v_cndmask_b32_e64 v4, v4, v6, s[18:19]
	v_cndmask_b32_e64 v5, v5, v7, s[18:19]
	v_cndmask_b32_e64 v8, v8, v10, s[98:99]
	v_cndmask_b32_e64 v9, v9, v11, s[98:99]
	v_cndmask_b32_e64 v12, v12, v14, s[100:101]
	v_cndmask_b32_e64 v13, v13, v15, s[100:101]
	v_cmp_gt_f32_e32 vcc, v4, v0
	v_cmp_gt_f32_e64 s[18:19], v12, v8
	s_nop 0
	v_cndmask_b32_e64 v0, v0, v4, vcc
	v_cndmask_b32_e64 v1, v1, v5, vcc
	v_cndmask_b32_e64 v8, v8, v12, s[18:19]
	v_cndmask_b32_e64 v9, v9, v13, s[18:19]
	v_cmp_gt_f32_e32 vcc, v8, v0
	s_nop 1
	v_cndmask_b32_e64 v0, v0, v8, vcc
	v_cndmask_b32_e64 v1, v1, v9, vcc
	v_mov_b32_e32 v255, v0
	v_mov_b32_e32 v16, 1.0
	v_lshlrev_b32_e32 v50, 2, v1
	v_lshrrev_b64 v[52:53], v50, v[48:49]
	v_lshl_add_u32 v51, v1, 7, v107
	v_and_b32_e32 v52, 15, v52
	v_lshl_add_u32 v52, v52, 7, v206
	ds_read_u8 v53, v51
	ds_read_u8 v54, v52 offset:40960
	v_lshlrev_b64 v[50:51], v50, 1
	v_lshl_add_u64 v[48:49], v[50:51], 0, v[48:49]
	v_bfe_u32 v0, v48, 0, 4
	v_bfe_u32 v1, v48, 4, 4
	v_bfe_u32 v2, v48, 8, 4
	v_bfe_u32 v3, v48, 12, 4
	v_bfe_u32 v4, v48, 16, 4
	v_bfe_u32 v5, v48, 20, 4
	v_bfe_u32 v6, v48, 24, 4
	v_bfe_u32 v7, v48, 28, 4
	v_bfe_u32 v8, v49, 0, 4
	v_bfe_u32 v9, v49, 4, 4
	v_bfe_u32 v10, v49, 8, 4
	v_bfe_u32 v11, v49, 12, 4
	v_bfe_u32 v12, v49, 16, 4
	v_bfe_u32 v13, v49, 20, 4
	v_bfe_u32 v14, v49, 24, 4
	v_bfe_u32 v15, v49, 28, 4
	v_lshl_add_u32 v0, v0, 9, v106
	v_lshl_add_u32 v1, v1, 9, v106
	v_lshl_add_u32 v2, v2, 9, v106
	v_lshl_add_u32 v3, v3, 9, v106
	v_lshl_add_u32 v4, v4, 9, v106
	v_lshl_add_u32 v5, v5, 9, v106
	v_lshl_add_u32 v6, v6, 9, v106
	v_lshl_add_u32 v7, v7, 9, v106
	v_lshl_add_u32 v8, v8, 9, v106
	v_lshl_add_u32 v9, v9, 9, v106
	v_lshl_add_u32 v10, v10, 9, v106
	v_lshl_add_u32 v11, v11, 9, v106
	v_lshl_add_u32 v12, v12, 9, v106
	v_lshl_add_u32 v13, v13, 9, v106
	v_lshl_add_u32 v14, v14, 9, v106
	v_lshl_add_u32 v15, v15, 9, v106
	s_waitcnt lgkmcnt(0)
	v_lshl_add_u32 v53, v53, 7, v54
	global_store_dword v254, v53, s[38:39] offset:0
	ds_read_b32 v0, v0 offset:32768
	ds_read_b32 v1, v1 offset:32768
	ds_read_b32 v2, v2 offset:32768
	ds_read_b32 v3, v3 offset:32768
	ds_read_b32 v4, v4 offset:32768
	ds_read_b32 v5, v5 offset:32768
	ds_read_b32 v6, v6 offset:32768
	ds_read_b32 v7, v7 offset:32768
	ds_read_b32 v8, v8 offset:32768
	ds_read_b32 v9, v9 offset:32768
	ds_read_b32 v10, v10 offset:32768
	ds_read_b32 v11, v11 offset:32768
	ds_read_b32 v12, v12 offset:32768
	ds_read_b32 v13, v13 offset:32768
	ds_read_b32 v14, v14 offset:32768
	ds_read_b32 v15, v15 offset:32768
	s_waitcnt lgkmcnt(0)
	v_add_f32_e32 v0, v32, v0
	v_add_f32_e32 v1, v33, v1
	v_add_f32_e32 v2, v34, v2
	v_add_f32_e32 v3, v35, v3
	v_add_f32_e32 v4, v36, v4
	v_add_f32_e32 v5, v37, v5
	v_add_f32_e32 v6, v38, v6
	v_add_f32_e32 v7, v39, v7
	v_add_f32_e32 v8, v40, v8
	v_add_f32_e32 v9, v41, v9
	v_add_f32_e32 v10, v42, v10
	v_add_f32_e32 v11, v43, v11
	v_add_f32_e32 v12, v44, v12
	v_add_f32_e32 v13, v45, v13
	v_add_f32_e32 v14, v46, v14
	v_add_f32_e32 v15, v47, v15
	v_cmp_gt_f32_e32 vcc, v1, v0
	v_cmp_gt_f32_e64 s[18:19], v3, v2
	v_cmp_gt_f32_e64 s[98:99], v5, v4
	v_cmp_gt_f32_e64 s[100:101], v7, v6
	v_cndmask_b32_e64 v0, v0, v1, vcc
	v_cndmask_b32_e64 v1, 0, 1, vcc
	v_cndmask_b32_e64 v2, v2, v3, s[18:19]
	v_cndmask_b32_e64 v3, 2, 3, s[18:19]
	v_cndmask_b32_e64 v4, v4, v5, s[98:99]
	v_cndmask_b32_e64 v5, 4, 5, s[98:99]
	v_cndmask_b32_e64 v6, v6, v7, s[100:101]
	v_cndmask_b32_e64 v7, 6, 7, s[100:101]
	v_cmp_gt_f32_e32 vcc, v9, v8
	v_cmp_gt_f32_e64 s[18:19], v11, v10
	v_cmp_gt_f32_e64 s[98:99], v13, v12
	v_cmp_gt_f32_e64 s[100:101], v15, v14
	v_cndmask_b32_e64 v8, v8, v9, vcc
	v_cndmask_b32_e64 v9, 8, 9, vcc
	v_cndmask_b32_e64 v10, v10, v11, s[18:19]
	v_cndmask_b32_e64 v11, 10, 11, s[18:19]
	v_cndmask_b32_e64 v12, v12, v13, s[98:99]
	v_cndmask_b32_e64 v13, 12, 13, s[98:99]
	v_cndmask_b32_e64 v14, v14, v15, s[100:101]
	v_cndmask_b32_e64 v15, 14, 15, s[100:101]
	v_cmp_gt_f32_e32 vcc, v2, v0
	v_cmp_gt_f32_e64 s[18:19], v6, v4
	v_cmp_gt_f32_e64 s[98:99], v10, v8
	v_cmp_gt_f32_e64 s[100:101], v14, v12
	v_cndmask_b32_e64 v0, v0, v2, vcc
	v_cndmask_b32_e64 v1, v1, v3, vcc
	v_cndmask_b32_e64 v4, v4, v6, s[18:19]
	v_cndmask_b32_e64 v5, v5, v7, s[18:19]
	v_cndmask_b32_e64 v8, v8, v10, s[98:99]
	v_cndmask_b32_e64 v9, v9, v11, s[98:99]
	v_cndmask_b32_e64 v12, v12, v14, s[100:101]
	v_cndmask_b32_e64 v13, v13, v15, s[100:101]
	v_cmp_gt_f32_e32 vcc, v4, v0
	v_cmp_gt_f32_e64 s[18:19], v12, v8
	s_nop 0
	v_cndmask_b32_e64 v0, v0, v4, vcc
	v_cndmask_b32_e64 v1, v1, v5, vcc
	v_cndmask_b32_e64 v8, v8, v12, s[18:19]
	v_cndmask_b32_e64 v9, v9, v13, s[18:19]
	v_cmp_gt_f32_e32 vcc, v8, v0
	s_nop 1
	v_cndmask_b32_e64 v0, v0, v8, vcc
	v_cndmask_b32_e64 v1, v1, v9, vcc
	v_sub_f32_e32 v17, v0, v255
	v_mul_f32_e32 v17, 0x3fb8aa3b, v17
	v_exp_f32_e32 v17, v17
	v_lshlrev_b32_e32 v50, 2, v1
	v_lshrrev_b64 v[52:53], v50, v[48:49]
	v_lshl_add_u32 v51, v1, 7, v107
	v_and_b32_e32 v52, 15, v52
	v_lshl_add_u32 v52, v52, 7, v206
	ds_read_u8 v53, v51
	ds_read_u8 v54, v52 offset:40960
	v_lshlrev_b64 v[50:51], v50, 1
	v_lshl_add_u64 v[48:49], v[50:51], 0, v[48:49]
	v_bfe_u32 v0, v48, 0, 4
	v_bfe_u32 v1, v48, 4, 4
	v_bfe_u32 v2, v48, 8, 4
	v_bfe_u32 v3, v48, 12, 4
	v_bfe_u32 v4, v48, 16, 4
	v_bfe_u32 v5, v48, 20, 4
	v_bfe_u32 v6, v48, 24, 4
	v_bfe_u32 v7, v48, 28, 4
	v_bfe_u32 v8, v49, 0, 4
	v_bfe_u32 v9, v49, 4, 4
	v_bfe_u32 v10, v49, 8, 4
	v_bfe_u32 v11, v49, 12, 4
	v_bfe_u32 v12, v49, 16, 4
	v_bfe_u32 v13, v49, 20, 4
	v_bfe_u32 v14, v49, 24, 4
	v_bfe_u32 v15, v49, 28, 4
	v_lshl_add_u32 v0, v0, 9, v106
	v_lshl_add_u32 v1, v1, 9, v106
	v_lshl_add_u32 v2, v2, 9, v106
	v_lshl_add_u32 v3, v3, 9, v106
	v_lshl_add_u32 v4, v4, 9, v106
	v_lshl_add_u32 v5, v5, 9, v106
	v_lshl_add_u32 v6, v6, 9, v106
	v_lshl_add_u32 v7, v7, 9, v106
	v_lshl_add_u32 v8, v8, 9, v106
	v_lshl_add_u32 v9, v9, 9, v106
	v_lshl_add_u32 v10, v10, 9, v106
	v_lshl_add_u32 v11, v11, 9, v106
	v_lshl_add_u32 v12, v12, 9, v106
	v_lshl_add_u32 v13, v13, 9, v106
	v_lshl_add_u32 v14, v14, 9, v106
	v_lshl_add_u32 v15, v15, 9, v106
	s_waitcnt lgkmcnt(0)
	v_lshl_add_u32 v53, v53, 7, v54
	global_store_dword v254, v53, s[38:39] offset:4
	ds_read_b32 v0, v0 offset:32768
	ds_read_b32 v1, v1 offset:32768
	ds_read_b32 v2, v2 offset:32768
	ds_read_b32 v3, v3 offset:32768
	ds_read_b32 v4, v4 offset:32768
	ds_read_b32 v5, v5 offset:32768
	ds_read_b32 v6, v6 offset:32768
	ds_read_b32 v7, v7 offset:32768
	ds_read_b32 v8, v8 offset:32768
	ds_read_b32 v9, v9 offset:32768
	ds_read_b32 v10, v10 offset:32768
	ds_read_b32 v11, v11 offset:32768
	ds_read_b32 v12, v12 offset:32768
	ds_read_b32 v13, v13 offset:32768
	ds_read_b32 v14, v14 offset:32768
	ds_read_b32 v15, v15 offset:32768
	s_waitcnt lgkmcnt(0)
	v_add_f32_e32 v0, v32, v0
	v_add_f32_e32 v1, v33, v1
	v_add_f32_e32 v2, v34, v2
	v_add_f32_e32 v3, v35, v3
	v_add_f32_e32 v4, v36, v4
	v_add_f32_e32 v5, v37, v5
	v_add_f32_e32 v6, v38, v6
	v_add_f32_e32 v7, v39, v7
	v_add_f32_e32 v8, v40, v8
	v_add_f32_e32 v9, v41, v9
	v_add_f32_e32 v10, v42, v10
	v_add_f32_e32 v11, v43, v11
	v_add_f32_e32 v12, v44, v12
	v_add_f32_e32 v13, v45, v13
	v_add_f32_e32 v14, v46, v14
	v_add_f32_e32 v15, v47, v15
	v_cmp_gt_f32_e32 vcc, v1, v0
	v_cmp_gt_f32_e64 s[18:19], v3, v2
	v_cmp_gt_f32_e64 s[98:99], v5, v4
	v_cmp_gt_f32_e64 s[100:101], v7, v6
	v_cndmask_b32_e64 v0, v0, v1, vcc
	v_cndmask_b32_e64 v1, 0, 1, vcc
	v_cndmask_b32_e64 v2, v2, v3, s[18:19]
	v_cndmask_b32_e64 v3, 2, 3, s[18:19]
	v_cndmask_b32_e64 v4, v4, v5, s[98:99]
	v_cndmask_b32_e64 v5, 4, 5, s[98:99]
	v_cndmask_b32_e64 v6, v6, v7, s[100:101]
	v_cndmask_b32_e64 v7, 6, 7, s[100:101]
	v_cmp_gt_f32_e32 vcc, v9, v8
	v_cmp_gt_f32_e64 s[18:19], v11, v10
	v_cmp_gt_f32_e64 s[98:99], v13, v12
	v_cmp_gt_f32_e64 s[100:101], v15, v14
	v_cndmask_b32_e64 v8, v8, v9, vcc
	v_cndmask_b32_e64 v9, 8, 9, vcc
	v_cndmask_b32_e64 v10, v10, v11, s[18:19]
	v_cndmask_b32_e64 v11, 10, 11, s[18:19]
	v_cndmask_b32_e64 v12, v12, v13, s[98:99]
	v_cndmask_b32_e64 v13, 12, 13, s[98:99]
	v_cndmask_b32_e64 v14, v14, v15, s[100:101]
	v_cndmask_b32_e64 v15, 14, 15, s[100:101]
	v_cmp_gt_f32_e32 vcc, v2, v0
	v_cmp_gt_f32_e64 s[18:19], v6, v4
	v_cmp_gt_f32_e64 s[98:99], v10, v8
	v_cmp_gt_f32_e64 s[100:101], v14, v12
	v_cndmask_b32_e64 v0, v0, v2, vcc
	v_cndmask_b32_e64 v1, v1, v3, vcc
	v_cndmask_b32_e64 v4, v4, v6, s[18:19]
	v_cndmask_b32_e64 v5, v5, v7, s[18:19]
	v_cndmask_b32_e64 v8, v8, v10, s[98:99]
	v_cndmask_b32_e64 v9, v9, v11, s[98:99]
	v_cndmask_b32_e64 v12, v12, v14, s[100:101]
	v_cndmask_b32_e64 v13, v13, v15, s[100:101]
	v_cmp_gt_f32_e32 vcc, v4, v0
	v_cmp_gt_f32_e64 s[18:19], v12, v8
	s_nop 0
	v_cndmask_b32_e64 v0, v0, v4, vcc
	v_cndmask_b32_e64 v1, v1, v5, vcc
	v_cndmask_b32_e64 v8, v8, v12, s[18:19]
	v_cndmask_b32_e64 v9, v9, v13, s[18:19]
	v_cmp_gt_f32_e32 vcc, v8, v0
	s_nop 1
	v_cndmask_b32_e64 v0, v0, v8, vcc
	v_cndmask_b32_e64 v1, v1, v9, vcc
	v_sub_f32_e32 v18, v0, v255
	v_mul_f32_e32 v18, 0x3fb8aa3b, v18
	v_exp_f32_e32 v18, v18
	v_lshlrev_b32_e32 v50, 2, v1
	v_lshrrev_b64 v[52:53], v50, v[48:49]
	v_lshl_add_u32 v51, v1, 7, v107
	v_and_b32_e32 v52, 15, v52
	v_lshl_add_u32 v52, v52, 7, v206
	ds_read_u8 v53, v51
	ds_read_u8 v54, v52 offset:40960
	v_lshlrev_b64 v[50:51], v50, 1
	v_lshl_add_u64 v[48:49], v[50:51], 0, v[48:49]
	v_bfe_u32 v0, v48, 0, 4
	v_bfe_u32 v1, v48, 4, 4
	v_bfe_u32 v2, v48, 8, 4
	v_bfe_u32 v3, v48, 12, 4
	v_bfe_u32 v4, v48, 16, 4
	v_bfe_u32 v5, v48, 20, 4
	v_bfe_u32 v6, v48, 24, 4
	v_bfe_u32 v7, v48, 28, 4
	v_bfe_u32 v8, v49, 0, 4
	v_bfe_u32 v9, v49, 4, 4
	v_bfe_u32 v10, v49, 8, 4
	v_bfe_u32 v11, v49, 12, 4
	v_bfe_u32 v12, v49, 16, 4
	v_bfe_u32 v13, v49, 20, 4
	v_bfe_u32 v14, v49, 24, 4
	v_bfe_u32 v15, v49, 28, 4
	v_lshl_add_u32 v0, v0, 9, v106
	v_lshl_add_u32 v1, v1, 9, v106
	v_lshl_add_u32 v2, v2, 9, v106
	v_lshl_add_u32 v3, v3, 9, v106
	v_lshl_add_u32 v4, v4, 9, v106
	v_lshl_add_u32 v5, v5, 9, v106
	v_lshl_add_u32 v6, v6, 9, v106
	v_lshl_add_u32 v7, v7, 9, v106
	v_lshl_add_u32 v8, v8, 9, v106
	v_lshl_add_u32 v9, v9, 9, v106
	v_lshl_add_u32 v10, v10, 9, v106
	v_lshl_add_u32 v11, v11, 9, v106
	v_lshl_add_u32 v12, v12, 9, v106
	v_lshl_add_u32 v13, v13, 9, v106
	v_lshl_add_u32 v14, v14, 9, v106
	v_lshl_add_u32 v15, v15, 9, v106
	s_waitcnt lgkmcnt(0)
	v_lshl_add_u32 v53, v53, 7, v54
	global_store_dword v254, v53, s[38:39] offset:8
	ds_read_b32 v0, v0 offset:32768
	ds_read_b32 v1, v1 offset:32768
	ds_read_b32 v2, v2 offset:32768
	ds_read_b32 v3, v3 offset:32768
	ds_read_b32 v4, v4 offset:32768
	ds_read_b32 v5, v5 offset:32768
	ds_read_b32 v6, v6 offset:32768
	ds_read_b32 v7, v7 offset:32768
	ds_read_b32 v8, v8 offset:32768
	ds_read_b32 v9, v9 offset:32768
	ds_read_b32 v10, v10 offset:32768
	ds_read_b32 v11, v11 offset:32768
	ds_read_b32 v12, v12 offset:32768
	ds_read_b32 v13, v13 offset:32768
	ds_read_b32 v14, v14 offset:32768
	ds_read_b32 v15, v15 offset:32768
	s_waitcnt lgkmcnt(0)
	v_add_f32_e32 v0, v32, v0
	v_add_f32_e32 v1, v33, v1
	v_add_f32_e32 v2, v34, v2
	v_add_f32_e32 v3, v35, v3
	v_add_f32_e32 v4, v36, v4
	v_add_f32_e32 v5, v37, v5
	v_add_f32_e32 v6, v38, v6
	v_add_f32_e32 v7, v39, v7
	v_add_f32_e32 v8, v40, v8
	v_add_f32_e32 v9, v41, v9
	v_add_f32_e32 v10, v42, v10
	v_add_f32_e32 v11, v43, v11
	v_add_f32_e32 v12, v44, v12
	v_add_f32_e32 v13, v45, v13
	v_add_f32_e32 v14, v46, v14
	v_add_f32_e32 v15, v47, v15
	v_cmp_gt_f32_e32 vcc, v1, v0
	v_cmp_gt_f32_e64 s[18:19], v3, v2
	v_cmp_gt_f32_e64 s[98:99], v5, v4
	v_cmp_gt_f32_e64 s[100:101], v7, v6
	v_cndmask_b32_e64 v0, v0, v1, vcc
	v_cndmask_b32_e64 v1, 0, 1, vcc
	v_cndmask_b32_e64 v2, v2, v3, s[18:19]
	v_cndmask_b32_e64 v3, 2, 3, s[18:19]
	v_cndmask_b32_e64 v4, v4, v5, s[98:99]
	v_cndmask_b32_e64 v5, 4, 5, s[98:99]
	v_cndmask_b32_e64 v6, v6, v7, s[100:101]
	v_cndmask_b32_e64 v7, 6, 7, s[100:101]
	v_cmp_gt_f32_e32 vcc, v9, v8
	v_cmp_gt_f32_e64 s[18:19], v11, v10
	v_cmp_gt_f32_e64 s[98:99], v13, v12
	v_cmp_gt_f32_e64 s[100:101], v15, v14
	v_cndmask_b32_e64 v8, v8, v9, vcc
	v_cndmask_b32_e64 v9, 8, 9, vcc
	v_cndmask_b32_e64 v10, v10, v11, s[18:19]
	v_cndmask_b32_e64 v11, 10, 11, s[18:19]
	v_cndmask_b32_e64 v12, v12, v13, s[98:99]
	v_cndmask_b32_e64 v13, 12, 13, s[98:99]
	v_cndmask_b32_e64 v14, v14, v15, s[100:101]
	v_cndmask_b32_e64 v15, 14, 15, s[100:101]
	v_cmp_gt_f32_e32 vcc, v2, v0
	v_cmp_gt_f32_e64 s[18:19], v6, v4
	v_cmp_gt_f32_e64 s[98:99], v10, v8
	v_cmp_gt_f32_e64 s[100:101], v14, v12
	v_cndmask_b32_e64 v0, v0, v2, vcc
	v_cndmask_b32_e64 v1, v1, v3, vcc
	v_cndmask_b32_e64 v4, v4, v6, s[18:19]
	v_cndmask_b32_e64 v5, v5, v7, s[18:19]
	v_cndmask_b32_e64 v8, v8, v10, s[98:99]
	v_cndmask_b32_e64 v9, v9, v11, s[98:99]
	v_cndmask_b32_e64 v12, v12, v14, s[100:101]
	v_cndmask_b32_e64 v13, v13, v15, s[100:101]
	v_cmp_gt_f32_e32 vcc, v4, v0
	v_cmp_gt_f32_e64 s[18:19], v12, v8
	s_nop 0
	v_cndmask_b32_e64 v0, v0, v4, vcc
	v_cndmask_b32_e64 v1, v1, v5, vcc
	v_cndmask_b32_e64 v8, v8, v12, s[18:19]
	v_cndmask_b32_e64 v9, v9, v13, s[18:19]
	v_cmp_gt_f32_e32 vcc, v8, v0
	s_nop 1
	v_cndmask_b32_e64 v0, v0, v8, vcc
	v_cndmask_b32_e64 v1, v1, v9, vcc
	v_sub_f32_e32 v19, v0, v255
	v_mul_f32_e32 v19, 0x3fb8aa3b, v19
	v_exp_f32_e32 v19, v19
	v_lshlrev_b32_e32 v50, 2, v1
	v_lshrrev_b64 v[52:53], v50, v[48:49]
	v_lshl_add_u32 v51, v1, 7, v107
	v_and_b32_e32 v52, 15, v52
	v_lshl_add_u32 v52, v52, 7, v206
	ds_read_u8 v53, v51
	ds_read_u8 v54, v52 offset:40960
	v_lshlrev_b64 v[50:51], v50, 1
	v_lshl_add_u64 v[48:49], v[50:51], 0, v[48:49]
	v_bfe_u32 v0, v48, 0, 4
	v_bfe_u32 v1, v48, 4, 4
	v_bfe_u32 v2, v48, 8, 4
	v_bfe_u32 v3, v48, 12, 4
	v_bfe_u32 v4, v48, 16, 4
	v_bfe_u32 v5, v48, 20, 4
	v_bfe_u32 v6, v48, 24, 4
	v_bfe_u32 v7, v48, 28, 4
	v_bfe_u32 v8, v49, 0, 4
	v_bfe_u32 v9, v49, 4, 4
	v_bfe_u32 v10, v49, 8, 4
	v_bfe_u32 v11, v49, 12, 4
	v_bfe_u32 v12, v49, 16, 4
	v_bfe_u32 v13, v49, 20, 4
	v_bfe_u32 v14, v49, 24, 4
	v_bfe_u32 v15, v49, 28, 4
	v_lshl_add_u32 v0, v0, 9, v106
	v_lshl_add_u32 v1, v1, 9, v106
	v_lshl_add_u32 v2, v2, 9, v106
	v_lshl_add_u32 v3, v3, 9, v106
	v_lshl_add_u32 v4, v4, 9, v106
	v_lshl_add_u32 v5, v5, 9, v106
	v_lshl_add_u32 v6, v6, 9, v106
	v_lshl_add_u32 v7, v7, 9, v106
	v_lshl_add_u32 v8, v8, 9, v106
	v_lshl_add_u32 v9, v9, 9, v106
	v_lshl_add_u32 v10, v10, 9, v106
	v_lshl_add_u32 v11, v11, 9, v106
	v_lshl_add_u32 v12, v12, 9, v106
	v_lshl_add_u32 v13, v13, 9, v106
	v_lshl_add_u32 v14, v14, 9, v106
	v_lshl_add_u32 v15, v15, 9, v106
	s_waitcnt lgkmcnt(0)
	v_lshl_add_u32 v53, v53, 7, v54
	global_store_dword v254, v53, s[38:39] offset:12
	ds_read_b32 v0, v0 offset:32768
	ds_read_b32 v1, v1 offset:32768
	ds_read_b32 v2, v2 offset:32768
	ds_read_b32 v3, v3 offset:32768
	ds_read_b32 v4, v4 offset:32768
	ds_read_b32 v5, v5 offset:32768
	ds_read_b32 v6, v6 offset:32768
	ds_read_b32 v7, v7 offset:32768
	ds_read_b32 v8, v8 offset:32768
	ds_read_b32 v9, v9 offset:32768
	ds_read_b32 v10, v10 offset:32768
	ds_read_b32 v11, v11 offset:32768
	ds_read_b32 v12, v12 offset:32768
	ds_read_b32 v13, v13 offset:32768
	ds_read_b32 v14, v14 offset:32768
	ds_read_b32 v15, v15 offset:32768
	s_waitcnt lgkmcnt(0)
	v_add_f32_e32 v0, v32, v0
	v_add_f32_e32 v1, v33, v1
	v_add_f32_e32 v2, v34, v2
	v_add_f32_e32 v3, v35, v3
	v_add_f32_e32 v4, v36, v4
	v_add_f32_e32 v5, v37, v5
	v_add_f32_e32 v6, v38, v6
	v_add_f32_e32 v7, v39, v7
	v_add_f32_e32 v8, v40, v8
	v_add_f32_e32 v9, v41, v9
	v_add_f32_e32 v10, v42, v10
	v_add_f32_e32 v11, v43, v11
	v_add_f32_e32 v12, v44, v12
	v_add_f32_e32 v13, v45, v13
	v_add_f32_e32 v14, v46, v14
	v_add_f32_e32 v15, v47, v15
	v_cmp_gt_f32_e32 vcc, v1, v0
	v_cmp_gt_f32_e64 s[18:19], v3, v2
	v_cmp_gt_f32_e64 s[98:99], v5, v4
	v_cmp_gt_f32_e64 s[100:101], v7, v6
	v_cndmask_b32_e64 v0, v0, v1, vcc
	v_cndmask_b32_e64 v1, 0, 1, vcc
	v_cndmask_b32_e64 v2, v2, v3, s[18:19]
	v_cndmask_b32_e64 v3, 2, 3, s[18:19]
	v_cndmask_b32_e64 v4, v4, v5, s[98:99]
	v_cndmask_b32_e64 v5, 4, 5, s[98:99]
	v_cndmask_b32_e64 v6, v6, v7, s[100:101]
	v_cndmask_b32_e64 v7, 6, 7, s[100:101]
	v_cmp_gt_f32_e32 vcc, v9, v8
	v_cmp_gt_f32_e64 s[18:19], v11, v10
	v_cmp_gt_f32_e64 s[98:99], v13, v12
	v_cmp_gt_f32_e64 s[100:101], v15, v14
	v_cndmask_b32_e64 v8, v8, v9, vcc
	v_cndmask_b32_e64 v9, 8, 9, vcc
	v_cndmask_b32_e64 v10, v10, v11, s[18:19]
	v_cndmask_b32_e64 v11, 10, 11, s[18:19]
	v_cndmask_b32_e64 v12, v12, v13, s[98:99]
	v_cndmask_b32_e64 v13, 12, 13, s[98:99]
	v_cndmask_b32_e64 v14, v14, v15, s[100:101]
	v_cndmask_b32_e64 v15, 14, 15, s[100:101]
	v_cmp_gt_f32_e32 vcc, v2, v0
	v_cmp_gt_f32_e64 s[18:19], v6, v4
	v_cmp_gt_f32_e64 s[98:99], v10, v8
	v_cmp_gt_f32_e64 s[100:101], v14, v12
	v_cndmask_b32_e64 v0, v0, v2, vcc
	v_cndmask_b32_e64 v1, v1, v3, vcc
	v_cndmask_b32_e64 v4, v4, v6, s[18:19]
	v_cndmask_b32_e64 v5, v5, v7, s[18:19]
	v_cndmask_b32_e64 v8, v8, v10, s[98:99]
	v_cndmask_b32_e64 v9, v9, v11, s[98:99]
	v_cndmask_b32_e64 v12, v12, v14, s[100:101]
	v_cndmask_b32_e64 v13, v13, v15, s[100:101]
	v_cmp_gt_f32_e32 vcc, v4, v0
	v_cmp_gt_f32_e64 s[18:19], v12, v8
	s_nop 0
	v_cndmask_b32_e64 v0, v0, v4, vcc
	v_cndmask_b32_e64 v1, v1, v5, vcc
	v_cndmask_b32_e64 v8, v8, v12, s[18:19]
	v_cndmask_b32_e64 v9, v9, v13, s[18:19]
	v_cmp_gt_f32_e32 vcc, v8, v0
	s_nop 1
	v_cndmask_b32_e64 v0, v0, v8, vcc
	v_cndmask_b32_e64 v1, v1, v9, vcc
	v_sub_f32_e32 v20, v0, v255
	v_mul_f32_e32 v20, 0x3fb8aa3b, v20
	v_exp_f32_e32 v20, v20
	v_lshlrev_b32_e32 v50, 2, v1
	v_lshrrev_b64 v[52:53], v50, v[48:49]
	v_lshl_add_u32 v51, v1, 7, v107
	v_and_b32_e32 v52, 15, v52
	v_lshl_add_u32 v52, v52, 7, v206
	ds_read_u8 v53, v51
	ds_read_u8 v54, v52 offset:40960
	v_lshlrev_b64 v[50:51], v50, 1
	v_lshl_add_u64 v[48:49], v[50:51], 0, v[48:49]
	v_bfe_u32 v0, v48, 0, 4
	v_bfe_u32 v1, v48, 4, 4
	v_bfe_u32 v2, v48, 8, 4
	v_bfe_u32 v3, v48, 12, 4
	v_bfe_u32 v4, v48, 16, 4
	v_bfe_u32 v5, v48, 20, 4
	v_bfe_u32 v6, v48, 24, 4
	v_bfe_u32 v7, v48, 28, 4
	v_bfe_u32 v8, v49, 0, 4
	v_bfe_u32 v9, v49, 4, 4
	v_bfe_u32 v10, v49, 8, 4
	v_bfe_u32 v11, v49, 12, 4
	v_bfe_u32 v12, v49, 16, 4
	v_bfe_u32 v13, v49, 20, 4
	v_bfe_u32 v14, v49, 24, 4
	v_bfe_u32 v15, v49, 28, 4
	v_lshl_add_u32 v0, v0, 9, v106
	v_lshl_add_u32 v1, v1, 9, v106
	v_lshl_add_u32 v2, v2, 9, v106
	v_lshl_add_u32 v3, v3, 9, v106
	v_lshl_add_u32 v4, v4, 9, v106
	v_lshl_add_u32 v5, v5, 9, v106
	v_lshl_add_u32 v6, v6, 9, v106
	v_lshl_add_u32 v7, v7, 9, v106
	v_lshl_add_u32 v8, v8, 9, v106
	v_lshl_add_u32 v9, v9, 9, v106
	v_lshl_add_u32 v10, v10, 9, v106
	v_lshl_add_u32 v11, v11, 9, v106
	v_lshl_add_u32 v12, v12, 9, v106
	v_lshl_add_u32 v13, v13, 9, v106
	v_lshl_add_u32 v14, v14, 9, v106
	v_lshl_add_u32 v15, v15, 9, v106
	s_waitcnt lgkmcnt(0)
	v_lshl_add_u32 v53, v53, 7, v54
	global_store_dword v254, v53, s[38:39] offset:16
	ds_read_b32 v0, v0 offset:32768
	ds_read_b32 v1, v1 offset:32768
	ds_read_b32 v2, v2 offset:32768
	ds_read_b32 v3, v3 offset:32768
	ds_read_b32 v4, v4 offset:32768
	ds_read_b32 v5, v5 offset:32768
	ds_read_b32 v6, v6 offset:32768
	ds_read_b32 v7, v7 offset:32768
	ds_read_b32 v8, v8 offset:32768
	ds_read_b32 v9, v9 offset:32768
	ds_read_b32 v10, v10 offset:32768
	ds_read_b32 v11, v11 offset:32768
	ds_read_b32 v12, v12 offset:32768
	ds_read_b32 v13, v13 offset:32768
	ds_read_b32 v14, v14 offset:32768
	ds_read_b32 v15, v15 offset:32768
	s_waitcnt lgkmcnt(0)
	v_add_f32_e32 v0, v32, v0
	v_add_f32_e32 v1, v33, v1
	v_add_f32_e32 v2, v34, v2
	v_add_f32_e32 v3, v35, v3
	v_add_f32_e32 v4, v36, v4
	v_add_f32_e32 v5, v37, v5
	v_add_f32_e32 v6, v38, v6
	v_add_f32_e32 v7, v39, v7
	v_add_f32_e32 v8, v40, v8
	v_add_f32_e32 v9, v41, v9
	v_add_f32_e32 v10, v42, v10
	v_add_f32_e32 v11, v43, v11
	v_add_f32_e32 v12, v44, v12
	v_add_f32_e32 v13, v45, v13
	v_add_f32_e32 v14, v46, v14
	v_add_f32_e32 v15, v47, v15
	v_cmp_gt_f32_e32 vcc, v1, v0
	v_cmp_gt_f32_e64 s[18:19], v3, v2
	v_cmp_gt_f32_e64 s[98:99], v5, v4
	v_cmp_gt_f32_e64 s[100:101], v7, v6
	v_cndmask_b32_e64 v0, v0, v1, vcc
	v_cndmask_b32_e64 v1, 0, 1, vcc
	v_cndmask_b32_e64 v2, v2, v3, s[18:19]
	v_cndmask_b32_e64 v3, 2, 3, s[18:19]
	v_cndmask_b32_e64 v4, v4, v5, s[98:99]
	v_cndmask_b32_e64 v5, 4, 5, s[98:99]
	v_cndmask_b32_e64 v6, v6, v7, s[100:101]
	v_cndmask_b32_e64 v7, 6, 7, s[100:101]
	v_cmp_gt_f32_e32 vcc, v9, v8
	v_cmp_gt_f32_e64 s[18:19], v11, v10
	v_cmp_gt_f32_e64 s[98:99], v13, v12
	v_cmp_gt_f32_e64 s[100:101], v15, v14
	v_cndmask_b32_e64 v8, v8, v9, vcc
	v_cndmask_b32_e64 v9, 8, 9, vcc
	v_cndmask_b32_e64 v10, v10, v11, s[18:19]
	v_cndmask_b32_e64 v11, 10, 11, s[18:19]
	v_cndmask_b32_e64 v12, v12, v13, s[98:99]
	v_cndmask_b32_e64 v13, 12, 13, s[98:99]
	v_cndmask_b32_e64 v14, v14, v15, s[100:101]
	v_cndmask_b32_e64 v15, 14, 15, s[100:101]
	v_cmp_gt_f32_e32 vcc, v2, v0
	v_cmp_gt_f32_e64 s[18:19], v6, v4
	v_cmp_gt_f32_e64 s[98:99], v10, v8
	v_cmp_gt_f32_e64 s[100:101], v14, v12
	v_cndmask_b32_e64 v0, v0, v2, vcc
	v_cndmask_b32_e64 v1, v1, v3, vcc
	v_cndmask_b32_e64 v4, v4, v6, s[18:19]
	v_cndmask_b32_e64 v5, v5, v7, s[18:19]
	v_cndmask_b32_e64 v8, v8, v10, s[98:99]
	v_cndmask_b32_e64 v9, v9, v11, s[98:99]
	v_cndmask_b32_e64 v12, v12, v14, s[100:101]
	v_cndmask_b32_e64 v13, v13, v15, s[100:101]
	v_cmp_gt_f32_e32 vcc, v4, v0
	v_cmp_gt_f32_e64 s[18:19], v12, v8
	s_nop 0
	v_cndmask_b32_e64 v0, v0, v4, vcc
	v_cndmask_b32_e64 v1, v1, v5, vcc
	v_cndmask_b32_e64 v8, v8, v12, s[18:19]
	v_cndmask_b32_e64 v9, v9, v13, s[18:19]
	v_cmp_gt_f32_e32 vcc, v8, v0
	s_nop 1
	v_cndmask_b32_e64 v0, v0, v8, vcc
	v_cndmask_b32_e64 v1, v1, v9, vcc
	v_sub_f32_e32 v21, v0, v255
	v_mul_f32_e32 v21, 0x3fb8aa3b, v21
	v_exp_f32_e32 v21, v21
	v_lshlrev_b32_e32 v50, 2, v1
	v_lshrrev_b64 v[52:53], v50, v[48:49]
	v_lshl_add_u32 v51, v1, 7, v107
	v_and_b32_e32 v52, 15, v52
	v_lshl_add_u32 v52, v52, 7, v206
	ds_read_u8 v53, v51
	ds_read_u8 v54, v52 offset:40960
	v_lshlrev_b64 v[50:51], v50, 1
	v_lshl_add_u64 v[48:49], v[50:51], 0, v[48:49]
	v_bfe_u32 v0, v48, 0, 4
	v_bfe_u32 v1, v48, 4, 4
	v_bfe_u32 v2, v48, 8, 4
	v_bfe_u32 v3, v48, 12, 4
	v_bfe_u32 v4, v48, 16, 4
	v_bfe_u32 v5, v48, 20, 4
	v_bfe_u32 v6, v48, 24, 4
	v_bfe_u32 v7, v48, 28, 4
	v_bfe_u32 v8, v49, 0, 4
	v_bfe_u32 v9, v49, 4, 4
	v_bfe_u32 v10, v49, 8, 4
	v_bfe_u32 v11, v49, 12, 4
	v_bfe_u32 v12, v49, 16, 4
	v_bfe_u32 v13, v49, 20, 4
	v_bfe_u32 v14, v49, 24, 4
	v_bfe_u32 v15, v49, 28, 4
	v_lshl_add_u32 v0, v0, 9, v106
	v_lshl_add_u32 v1, v1, 9, v106
	v_lshl_add_u32 v2, v2, 9, v106
	v_lshl_add_u32 v3, v3, 9, v106
	v_lshl_add_u32 v4, v4, 9, v106
	v_lshl_add_u32 v5, v5, 9, v106
	v_lshl_add_u32 v6, v6, 9, v106
	v_lshl_add_u32 v7, v7, 9, v106
	v_lshl_add_u32 v8, v8, 9, v106
	v_lshl_add_u32 v9, v9, 9, v106
	v_lshl_add_u32 v10, v10, 9, v106
	v_lshl_add_u32 v11, v11, 9, v106
	v_lshl_add_u32 v12, v12, 9, v106
	v_lshl_add_u32 v13, v13, 9, v106
	v_lshl_add_u32 v14, v14, 9, v106
	v_lshl_add_u32 v15, v15, 9, v106
	s_waitcnt lgkmcnt(0)
	v_lshl_add_u32 v53, v53, 7, v54
	global_store_dword v254, v53, s[38:39] offset:20
	ds_read_b32 v0, v0 offset:32768
	ds_read_b32 v1, v1 offset:32768
	ds_read_b32 v2, v2 offset:32768
	ds_read_b32 v3, v3 offset:32768
	ds_read_b32 v4, v4 offset:32768
	ds_read_b32 v5, v5 offset:32768
	ds_read_b32 v6, v6 offset:32768
	ds_read_b32 v7, v7 offset:32768
	ds_read_b32 v8, v8 offset:32768
	ds_read_b32 v9, v9 offset:32768
	ds_read_b32 v10, v10 offset:32768
	ds_read_b32 v11, v11 offset:32768
	ds_read_b32 v12, v12 offset:32768
	ds_read_b32 v13, v13 offset:32768
	ds_read_b32 v14, v14 offset:32768
	ds_read_b32 v15, v15 offset:32768
	s_waitcnt lgkmcnt(0)
	v_add_f32_e32 v0, v32, v0
	v_add_f32_e32 v1, v33, v1
	v_add_f32_e32 v2, v34, v2
	v_add_f32_e32 v3, v35, v3
	v_add_f32_e32 v4, v36, v4
	v_add_f32_e32 v5, v37, v5
	v_add_f32_e32 v6, v38, v6
	v_add_f32_e32 v7, v39, v7
	v_add_f32_e32 v8, v40, v8
	v_add_f32_e32 v9, v41, v9
	v_add_f32_e32 v10, v42, v10
	v_add_f32_e32 v11, v43, v11
	v_add_f32_e32 v12, v44, v12
	v_add_f32_e32 v13, v45, v13
	v_add_f32_e32 v14, v46, v14
	v_add_f32_e32 v15, v47, v15
	v_cmp_gt_f32_e32 vcc, v1, v0
	v_cmp_gt_f32_e64 s[18:19], v3, v2
	v_cmp_gt_f32_e64 s[98:99], v5, v4
	v_cmp_gt_f32_e64 s[100:101], v7, v6
	v_cndmask_b32_e64 v0, v0, v1, vcc
	v_cndmask_b32_e64 v1, 0, 1, vcc
	v_cndmask_b32_e64 v2, v2, v3, s[18:19]
	v_cndmask_b32_e64 v3, 2, 3, s[18:19]
	v_cndmask_b32_e64 v4, v4, v5, s[98:99]
	v_cndmask_b32_e64 v5, 4, 5, s[98:99]
	v_cndmask_b32_e64 v6, v6, v7, s[100:101]
	v_cndmask_b32_e64 v7, 6, 7, s[100:101]
	v_cmp_gt_f32_e32 vcc, v9, v8
	v_cmp_gt_f32_e64 s[18:19], v11, v10
	v_cmp_gt_f32_e64 s[98:99], v13, v12
	v_cmp_gt_f32_e64 s[100:101], v15, v14
	v_cndmask_b32_e64 v8, v8, v9, vcc
	v_cndmask_b32_e64 v9, 8, 9, vcc
	v_cndmask_b32_e64 v10, v10, v11, s[18:19]
	v_cndmask_b32_e64 v11, 10, 11, s[18:19]
	v_cndmask_b32_e64 v12, v12, v13, s[98:99]
	v_cndmask_b32_e64 v13, 12, 13, s[98:99]
	v_cndmask_b32_e64 v14, v14, v15, s[100:101]
	v_cndmask_b32_e64 v15, 14, 15, s[100:101]
	v_cmp_gt_f32_e32 vcc, v2, v0
	v_cmp_gt_f32_e64 s[18:19], v6, v4
	v_cmp_gt_f32_e64 s[98:99], v10, v8
	v_cmp_gt_f32_e64 s[100:101], v14, v12
	v_cndmask_b32_e64 v0, v0, v2, vcc
	v_cndmask_b32_e64 v1, v1, v3, vcc
	v_cndmask_b32_e64 v4, v4, v6, s[18:19]
	v_cndmask_b32_e64 v5, v5, v7, s[18:19]
	v_cndmask_b32_e64 v8, v8, v10, s[98:99]
	v_cndmask_b32_e64 v9, v9, v11, s[98:99]
	v_cndmask_b32_e64 v12, v12, v14, s[100:101]
	v_cndmask_b32_e64 v13, v13, v15, s[100:101]
	v_cmp_gt_f32_e32 vcc, v4, v0
	v_cmp_gt_f32_e64 s[18:19], v12, v8
	s_nop 0
	v_cndmask_b32_e64 v0, v0, v4, vcc
	v_cndmask_b32_e64 v1, v1, v5, vcc
	v_cndmask_b32_e64 v8, v8, v12, s[18:19]
	v_cndmask_b32_e64 v9, v9, v13, s[18:19]
	v_cmp_gt_f32_e32 vcc, v8, v0
	s_nop 1
	v_cndmask_b32_e64 v0, v0, v8, vcc
	v_cndmask_b32_e64 v1, v1, v9, vcc
	v_sub_f32_e32 v22, v0, v255
	v_mul_f32_e32 v22, 0x3fb8aa3b, v22
	v_exp_f32_e32 v22, v22
	v_lshlrev_b32_e32 v50, 2, v1
	v_lshrrev_b64 v[52:53], v50, v[48:49]
	v_lshl_add_u32 v51, v1, 7, v107
	v_and_b32_e32 v52, 15, v52
	v_lshl_add_u32 v52, v52, 7, v206
	ds_read_u8 v53, v51
	ds_read_u8 v54, v52 offset:40960
	v_lshlrev_b64 v[50:51], v50, 1
	v_lshl_add_u64 v[48:49], v[50:51], 0, v[48:49]
	v_bfe_u32 v0, v48, 0, 4
	v_bfe_u32 v1, v48, 4, 4
	v_bfe_u32 v2, v48, 8, 4
	v_bfe_u32 v3, v48, 12, 4
	v_bfe_u32 v4, v48, 16, 4
	v_bfe_u32 v5, v48, 20, 4
	v_bfe_u32 v6, v48, 24, 4
	v_bfe_u32 v7, v48, 28, 4
	v_bfe_u32 v8, v49, 0, 4
	v_bfe_u32 v9, v49, 4, 4
	v_bfe_u32 v10, v49, 8, 4
	v_bfe_u32 v11, v49, 12, 4
	v_bfe_u32 v12, v49, 16, 4
	v_bfe_u32 v13, v49, 20, 4
	v_bfe_u32 v14, v49, 24, 4
	v_bfe_u32 v15, v49, 28, 4
	v_lshl_add_u32 v0, v0, 9, v106
	v_lshl_add_u32 v1, v1, 9, v106
	v_lshl_add_u32 v2, v2, 9, v106
	v_lshl_add_u32 v3, v3, 9, v106
	v_lshl_add_u32 v4, v4, 9, v106
	v_lshl_add_u32 v5, v5, 9, v106
	v_lshl_add_u32 v6, v6, 9, v106
	v_lshl_add_u32 v7, v7, 9, v106
	v_lshl_add_u32 v8, v8, 9, v106
	v_lshl_add_u32 v9, v9, 9, v106
	v_lshl_add_u32 v10, v10, 9, v106
	v_lshl_add_u32 v11, v11, 9, v106
	v_lshl_add_u32 v12, v12, 9, v106
	v_lshl_add_u32 v13, v13, 9, v106
	v_lshl_add_u32 v14, v14, 9, v106
	v_lshl_add_u32 v15, v15, 9, v106
	s_waitcnt lgkmcnt(0)
	v_lshl_add_u32 v53, v53, 7, v54
	global_store_dword v254, v53, s[38:39] offset:24
	ds_read_b32 v0, v0 offset:32768
	ds_read_b32 v1, v1 offset:32768
	ds_read_b32 v2, v2 offset:32768
	ds_read_b32 v3, v3 offset:32768
	ds_read_b32 v4, v4 offset:32768
	ds_read_b32 v5, v5 offset:32768
	ds_read_b32 v6, v6 offset:32768
	ds_read_b32 v7, v7 offset:32768
	ds_read_b32 v8, v8 offset:32768
	ds_read_b32 v9, v9 offset:32768
	ds_read_b32 v10, v10 offset:32768
	ds_read_b32 v11, v11 offset:32768
	ds_read_b32 v12, v12 offset:32768
	ds_read_b32 v13, v13 offset:32768
	ds_read_b32 v14, v14 offset:32768
	ds_read_b32 v15, v15 offset:32768
	s_waitcnt lgkmcnt(0)
	v_add_f32_e32 v0, v32, v0
	v_add_f32_e32 v1, v33, v1
	v_add_f32_e32 v2, v34, v2
	v_add_f32_e32 v3, v35, v3
	v_add_f32_e32 v4, v36, v4
	v_add_f32_e32 v5, v37, v5
	v_add_f32_e32 v6, v38, v6
	v_add_f32_e32 v7, v39, v7
	v_add_f32_e32 v8, v40, v8
	v_add_f32_e32 v9, v41, v9
	v_add_f32_e32 v10, v42, v10
	v_add_f32_e32 v11, v43, v11
	v_add_f32_e32 v12, v44, v12
	v_add_f32_e32 v13, v45, v13
	v_add_f32_e32 v14, v46, v14
	v_add_f32_e32 v15, v47, v15
	v_cmp_gt_f32_e32 vcc, v1, v0
	v_cmp_gt_f32_e64 s[18:19], v3, v2
	v_cmp_gt_f32_e64 s[98:99], v5, v4
	v_cmp_gt_f32_e64 s[100:101], v7, v6
	v_cndmask_b32_e64 v0, v0, v1, vcc
	v_cndmask_b32_e64 v1, 0, 1, vcc
	v_cndmask_b32_e64 v2, v2, v3, s[18:19]
	v_cndmask_b32_e64 v3, 2, 3, s[18:19]
	v_cndmask_b32_e64 v4, v4, v5, s[98:99]
	v_cndmask_b32_e64 v5, 4, 5, s[98:99]
	v_cndmask_b32_e64 v6, v6, v7, s[100:101]
	v_cndmask_b32_e64 v7, 6, 7, s[100:101]
	v_cmp_gt_f32_e32 vcc, v9, v8
	v_cmp_gt_f32_e64 s[18:19], v11, v10
	v_cmp_gt_f32_e64 s[98:99], v13, v12
	v_cmp_gt_f32_e64 s[100:101], v15, v14
	v_cndmask_b32_e64 v8, v8, v9, vcc
	v_cndmask_b32_e64 v9, 8, 9, vcc
	v_cndmask_b32_e64 v10, v10, v11, s[18:19]
	v_cndmask_b32_e64 v11, 10, 11, s[18:19]
	v_cndmask_b32_e64 v12, v12, v13, s[98:99]
	v_cndmask_b32_e64 v13, 12, 13, s[98:99]
	v_cndmask_b32_e64 v14, v14, v15, s[100:101]
	v_cndmask_b32_e64 v15, 14, 15, s[100:101]
	v_cmp_gt_f32_e32 vcc, v2, v0
	v_cmp_gt_f32_e64 s[18:19], v6, v4
	v_cmp_gt_f32_e64 s[98:99], v10, v8
	v_cmp_gt_f32_e64 s[100:101], v14, v12
	v_cndmask_b32_e64 v0, v0, v2, vcc
	v_cndmask_b32_e64 v1, v1, v3, vcc
	v_cndmask_b32_e64 v4, v4, v6, s[18:19]
	v_cndmask_b32_e64 v5, v5, v7, s[18:19]
	v_cndmask_b32_e64 v8, v8, v10, s[98:99]
	v_cndmask_b32_e64 v9, v9, v11, s[98:99]
	v_cndmask_b32_e64 v12, v12, v14, s[100:101]
	v_cndmask_b32_e64 v13, v13, v15, s[100:101]
	v_cmp_gt_f32_e32 vcc, v4, v0
	v_cmp_gt_f32_e64 s[18:19], v12, v8
	s_nop 0
	v_cndmask_b32_e64 v0, v0, v4, vcc
	v_cndmask_b32_e64 v1, v1, v5, vcc
	v_cndmask_b32_e64 v8, v8, v12, s[18:19]
	v_cndmask_b32_e64 v9, v9, v13, s[18:19]
	v_cmp_gt_f32_e32 vcc, v8, v0
	s_nop 1
	v_cndmask_b32_e64 v0, v0, v8, vcc
	v_cndmask_b32_e64 v1, v1, v9, vcc
	v_sub_f32_e32 v23, v0, v255
	v_mul_f32_e32 v23, 0x3fb8aa3b, v23
	v_exp_f32_e32 v23, v23
	v_lshlrev_b32_e32 v50, 2, v1
	v_lshrrev_b64 v[52:53], v50, v[48:49]
	v_lshl_add_u32 v51, v1, 7, v107
	v_and_b32_e32 v52, 15, v52
	v_lshl_add_u32 v52, v52, 7, v206
	ds_read_u8 v53, v51
	ds_read_u8 v54, v52 offset:40960
	v_lshlrev_b64 v[50:51], v50, 1
	v_lshl_add_u64 v[48:49], v[50:51], 0, v[48:49]
	v_bfe_u32 v0, v48, 0, 4
	v_bfe_u32 v1, v48, 4, 4
	v_bfe_u32 v2, v48, 8, 4
	v_bfe_u32 v3, v48, 12, 4
	v_bfe_u32 v4, v48, 16, 4
	v_bfe_u32 v5, v48, 20, 4
	v_bfe_u32 v6, v48, 24, 4
	v_bfe_u32 v7, v48, 28, 4
	v_bfe_u32 v8, v49, 0, 4
	v_bfe_u32 v9, v49, 4, 4
	v_bfe_u32 v10, v49, 8, 4
	v_bfe_u32 v11, v49, 12, 4
	v_bfe_u32 v12, v49, 16, 4
	v_bfe_u32 v13, v49, 20, 4
	v_bfe_u32 v14, v49, 24, 4
	v_bfe_u32 v15, v49, 28, 4
	v_lshl_add_u32 v0, v0, 9, v106
	v_lshl_add_u32 v1, v1, 9, v106
	v_lshl_add_u32 v2, v2, 9, v106
	v_lshl_add_u32 v3, v3, 9, v106
	v_lshl_add_u32 v4, v4, 9, v106
	v_lshl_add_u32 v5, v5, 9, v106
	v_lshl_add_u32 v6, v6, 9, v106
	v_lshl_add_u32 v7, v7, 9, v106
	v_lshl_add_u32 v8, v8, 9, v106
	v_lshl_add_u32 v9, v9, 9, v106
	v_lshl_add_u32 v10, v10, 9, v106
	v_lshl_add_u32 v11, v11, 9, v106
	v_lshl_add_u32 v12, v12, 9, v106
	v_lshl_add_u32 v13, v13, 9, v106
	v_lshl_add_u32 v14, v14, 9, v106
	v_lshl_add_u32 v15, v15, 9, v106
	s_waitcnt lgkmcnt(0)
	v_lshl_add_u32 v53, v53, 7, v54
	global_store_dword v254, v53, s[38:39] offset:28
	ds_read_b32 v0, v0 offset:32768
	ds_read_b32 v1, v1 offset:32768
	ds_read_b32 v2, v2 offset:32768
	ds_read_b32 v3, v3 offset:32768
	ds_read_b32 v4, v4 offset:32768
	ds_read_b32 v5, v5 offset:32768
	ds_read_b32 v6, v6 offset:32768
	ds_read_b32 v7, v7 offset:32768
	ds_read_b32 v8, v8 offset:32768
	ds_read_b32 v9, v9 offset:32768
	ds_read_b32 v10, v10 offset:32768
	ds_read_b32 v11, v11 offset:32768
	ds_read_b32 v12, v12 offset:32768
	ds_read_b32 v13, v13 offset:32768
	ds_read_b32 v14, v14 offset:32768
	ds_read_b32 v15, v15 offset:32768
	s_waitcnt lgkmcnt(0)
	v_add_f32_e32 v0, v32, v0
	v_add_f32_e32 v1, v33, v1
	v_add_f32_e32 v2, v34, v2
	v_add_f32_e32 v3, v35, v3
	v_add_f32_e32 v4, v36, v4
	v_add_f32_e32 v5, v37, v5
	v_add_f32_e32 v6, v38, v6
	v_add_f32_e32 v7, v39, v7
	v_add_f32_e32 v8, v40, v8
	v_add_f32_e32 v9, v41, v9
	v_add_f32_e32 v10, v42, v10
	v_add_f32_e32 v11, v43, v11
	v_add_f32_e32 v12, v44, v12
	v_add_f32_e32 v13, v45, v13
	v_add_f32_e32 v14, v46, v14
	v_add_f32_e32 v15, v47, v15
	v_cmp_gt_f32_e32 vcc, v1, v0
	v_cmp_gt_f32_e64 s[18:19], v3, v2
	v_cmp_gt_f32_e64 s[98:99], v5, v4
	v_cmp_gt_f32_e64 s[100:101], v7, v6
	v_cndmask_b32_e64 v0, v0, v1, vcc
	v_cndmask_b32_e64 v1, 0, 1, vcc
	v_cndmask_b32_e64 v2, v2, v3, s[18:19]
	v_cndmask_b32_e64 v3, 2, 3, s[18:19]
	v_cndmask_b32_e64 v4, v4, v5, s[98:99]
	v_cndmask_b32_e64 v5, 4, 5, s[98:99]
	v_cndmask_b32_e64 v6, v6, v7, s[100:101]
	v_cndmask_b32_e64 v7, 6, 7, s[100:101]
	v_cmp_gt_f32_e32 vcc, v9, v8
	v_cmp_gt_f32_e64 s[18:19], v11, v10
	v_cmp_gt_f32_e64 s[98:99], v13, v12
	v_cmp_gt_f32_e64 s[100:101], v15, v14
	v_cndmask_b32_e64 v8, v8, v9, vcc
	v_cndmask_b32_e64 v9, 8, 9, vcc
	v_cndmask_b32_e64 v10, v10, v11, s[18:19]
	v_cndmask_b32_e64 v11, 10, 11, s[18:19]
	v_cndmask_b32_e64 v12, v12, v13, s[98:99]
	v_cndmask_b32_e64 v13, 12, 13, s[98:99]
	v_cndmask_b32_e64 v14, v14, v15, s[100:101]
	v_cndmask_b32_e64 v15, 14, 15, s[100:101]
	v_cmp_gt_f32_e32 vcc, v2, v0
	v_cmp_gt_f32_e64 s[18:19], v6, v4
	v_cmp_gt_f32_e64 s[98:99], v10, v8
	v_cmp_gt_f32_e64 s[100:101], v14, v12
	v_cndmask_b32_e64 v0, v0, v2, vcc
	v_cndmask_b32_e64 v1, v1, v3, vcc
	v_cndmask_b32_e64 v4, v4, v6, s[18:19]
	v_cndmask_b32_e64 v5, v5, v7, s[18:19]
	v_cndmask_b32_e64 v8, v8, v10, s[98:99]
	v_cndmask_b32_e64 v9, v9, v11, s[98:99]
	v_cndmask_b32_e64 v12, v12, v14, s[100:101]
	v_cndmask_b32_e64 v13, v13, v15, s[100:101]
	v_cmp_gt_f32_e32 vcc, v4, v0
	v_cmp_gt_f32_e64 s[18:19], v12, v8
	s_nop 0
	v_cndmask_b32_e64 v0, v0, v4, vcc
	v_cndmask_b32_e64 v1, v1, v5, vcc
	v_cndmask_b32_e64 v8, v8, v12, s[18:19]
	v_cndmask_b32_e64 v9, v9, v13, s[18:19]
	v_cmp_gt_f32_e32 vcc, v8, v0
	s_nop 1
	v_cndmask_b32_e64 v0, v0, v8, vcc
	v_cndmask_b32_e64 v1, v1, v9, vcc
	v_sub_f32_e32 v24, v0, v255
	v_mul_f32_e32 v24, 0x3fb8aa3b, v24
	v_exp_f32_e32 v24, v24
	v_lshlrev_b32_e32 v50, 2, v1
	v_lshrrev_b64 v[52:53], v50, v[48:49]
	v_lshl_add_u32 v51, v1, 7, v107
	v_and_b32_e32 v52, 15, v52
	v_lshl_add_u32 v52, v52, 7, v206
	ds_read_u8 v53, v51
	ds_read_u8 v54, v52 offset:40960
	v_lshlrev_b64 v[50:51], v50, 1
	v_lshl_add_u64 v[48:49], v[50:51], 0, v[48:49]
	v_bfe_u32 v0, v48, 0, 4
	v_bfe_u32 v1, v48, 4, 4
	v_bfe_u32 v2, v48, 8, 4
	v_bfe_u32 v3, v48, 12, 4
	v_bfe_u32 v4, v48, 16, 4
	v_bfe_u32 v5, v48, 20, 4
	v_bfe_u32 v6, v48, 24, 4
	v_bfe_u32 v7, v48, 28, 4
	v_bfe_u32 v8, v49, 0, 4
	v_bfe_u32 v9, v49, 4, 4
	v_bfe_u32 v10, v49, 8, 4
	v_bfe_u32 v11, v49, 12, 4
	v_bfe_u32 v12, v49, 16, 4
	v_bfe_u32 v13, v49, 20, 4
	v_bfe_u32 v14, v49, 24, 4
	v_bfe_u32 v15, v49, 28, 4
	v_lshl_add_u32 v0, v0, 9, v106
	v_lshl_add_u32 v1, v1, 9, v106
	v_lshl_add_u32 v2, v2, 9, v106
	v_lshl_add_u32 v3, v3, 9, v106
	v_lshl_add_u32 v4, v4, 9, v106
	v_lshl_add_u32 v5, v5, 9, v106
	v_lshl_add_u32 v6, v6, 9, v106
	v_lshl_add_u32 v7, v7, 9, v106
	v_lshl_add_u32 v8, v8, 9, v106
	v_lshl_add_u32 v9, v9, 9, v106
	v_lshl_add_u32 v10, v10, 9, v106
	v_lshl_add_u32 v11, v11, 9, v106
	v_lshl_add_u32 v12, v12, 9, v106
	v_lshl_add_u32 v13, v13, 9, v106
	v_lshl_add_u32 v14, v14, 9, v106
	v_lshl_add_u32 v15, v15, 9, v106
	s_waitcnt lgkmcnt(0)
	v_lshl_add_u32 v53, v53, 7, v54
	global_store_dword v254, v53, s[38:39] offset:32
	ds_read_b32 v0, v0 offset:32768
	ds_read_b32 v1, v1 offset:32768
	ds_read_b32 v2, v2 offset:32768
	ds_read_b32 v3, v3 offset:32768
	ds_read_b32 v4, v4 offset:32768
	ds_read_b32 v5, v5 offset:32768
	ds_read_b32 v6, v6 offset:32768
	ds_read_b32 v7, v7 offset:32768
	ds_read_b32 v8, v8 offset:32768
	ds_read_b32 v9, v9 offset:32768
	ds_read_b32 v10, v10 offset:32768
	ds_read_b32 v11, v11 offset:32768
	ds_read_b32 v12, v12 offset:32768
	ds_read_b32 v13, v13 offset:32768
	ds_read_b32 v14, v14 offset:32768
	ds_read_b32 v15, v15 offset:32768
	s_waitcnt lgkmcnt(0)
	v_add_f32_e32 v0, v32, v0
	v_add_f32_e32 v1, v33, v1
	v_add_f32_e32 v2, v34, v2
	v_add_f32_e32 v3, v35, v3
	v_add_f32_e32 v4, v36, v4
	v_add_f32_e32 v5, v37, v5
	v_add_f32_e32 v6, v38, v6
	v_add_f32_e32 v7, v39, v7
	v_add_f32_e32 v8, v40, v8
	v_add_f32_e32 v9, v41, v9
	v_add_f32_e32 v10, v42, v10
	v_add_f32_e32 v11, v43, v11
	v_add_f32_e32 v12, v44, v12
	v_add_f32_e32 v13, v45, v13
	v_add_f32_e32 v14, v46, v14
	v_add_f32_e32 v15, v47, v15
	v_cmp_gt_f32_e32 vcc, v1, v0
	v_cmp_gt_f32_e64 s[18:19], v3, v2
	v_cmp_gt_f32_e64 s[98:99], v5, v4
	v_cmp_gt_f32_e64 s[100:101], v7, v6
	v_cndmask_b32_e64 v0, v0, v1, vcc
	v_cndmask_b32_e64 v1, 0, 1, vcc
	v_cndmask_b32_e64 v2, v2, v3, s[18:19]
	v_cndmask_b32_e64 v3, 2, 3, s[18:19]
	v_cndmask_b32_e64 v4, v4, v5, s[98:99]
	v_cndmask_b32_e64 v5, 4, 5, s[98:99]
	v_cndmask_b32_e64 v6, v6, v7, s[100:101]
	v_cndmask_b32_e64 v7, 6, 7, s[100:101]
	v_cmp_gt_f32_e32 vcc, v9, v8
	v_cmp_gt_f32_e64 s[18:19], v11, v10
	v_cmp_gt_f32_e64 s[98:99], v13, v12
	v_cmp_gt_f32_e64 s[100:101], v15, v14
	v_cndmask_b32_e64 v8, v8, v9, vcc
	v_cndmask_b32_e64 v9, 8, 9, vcc
	v_cndmask_b32_e64 v10, v10, v11, s[18:19]
	v_cndmask_b32_e64 v11, 10, 11, s[18:19]
	v_cndmask_b32_e64 v12, v12, v13, s[98:99]
	v_cndmask_b32_e64 v13, 12, 13, s[98:99]
	v_cndmask_b32_e64 v14, v14, v15, s[100:101]
	v_cndmask_b32_e64 v15, 14, 15, s[100:101]
	v_cmp_gt_f32_e32 vcc, v2, v0
	v_cmp_gt_f32_e64 s[18:19], v6, v4
	v_cmp_gt_f32_e64 s[98:99], v10, v8
	v_cmp_gt_f32_e64 s[100:101], v14, v12
	v_cndmask_b32_e64 v0, v0, v2, vcc
	v_cndmask_b32_e64 v1, v1, v3, vcc
	v_cndmask_b32_e64 v4, v4, v6, s[18:19]
	v_cndmask_b32_e64 v5, v5, v7, s[18:19]
	v_cndmask_b32_e64 v8, v8, v10, s[98:99]
	v_cndmask_b32_e64 v9, v9, v11, s[98:99]
	v_cndmask_b32_e64 v12, v12, v14, s[100:101]
	v_cndmask_b32_e64 v13, v13, v15, s[100:101]
	v_cmp_gt_f32_e32 vcc, v4, v0
	v_cmp_gt_f32_e64 s[18:19], v12, v8
	s_nop 0
	v_cndmask_b32_e64 v0, v0, v4, vcc
	v_cndmask_b32_e64 v1, v1, v5, vcc
	v_cndmask_b32_e64 v8, v8, v12, s[18:19]
	v_cndmask_b32_e64 v9, v9, v13, s[18:19]
	v_cmp_gt_f32_e32 vcc, v8, v0
	s_nop 1
	v_cndmask_b32_e64 v0, v0, v8, vcc
	v_cndmask_b32_e64 v1, v1, v9, vcc
	v_sub_f32_e32 v25, v0, v255
	v_mul_f32_e32 v25, 0x3fb8aa3b, v25
	v_exp_f32_e32 v25, v25
	v_lshlrev_b32_e32 v50, 2, v1
	v_lshrrev_b64 v[52:53], v50, v[48:49]
	v_lshl_add_u32 v51, v1, 7, v107
	v_and_b32_e32 v52, 15, v52
	v_lshl_add_u32 v52, v52, 7, v206
	ds_read_u8 v53, v51
	ds_read_u8 v54, v52 offset:40960
	v_lshlrev_b64 v[50:51], v50, 1
	v_lshl_add_u64 v[48:49], v[50:51], 0, v[48:49]
	v_bfe_u32 v0, v48, 0, 4
	v_bfe_u32 v1, v48, 4, 4
	v_bfe_u32 v2, v48, 8, 4
	v_bfe_u32 v3, v48, 12, 4
	v_bfe_u32 v4, v48, 16, 4
	v_bfe_u32 v5, v48, 20, 4
	v_bfe_u32 v6, v48, 24, 4
	v_bfe_u32 v7, v48, 28, 4
	v_bfe_u32 v8, v49, 0, 4
	v_bfe_u32 v9, v49, 4, 4
	v_bfe_u32 v10, v49, 8, 4
	v_bfe_u32 v11, v49, 12, 4
	v_bfe_u32 v12, v49, 16, 4
	v_bfe_u32 v13, v49, 20, 4
	v_bfe_u32 v14, v49, 24, 4
	v_bfe_u32 v15, v49, 28, 4
	v_lshl_add_u32 v0, v0, 9, v106
	v_lshl_add_u32 v1, v1, 9, v106
	v_lshl_add_u32 v2, v2, 9, v106
	v_lshl_add_u32 v3, v3, 9, v106
	v_lshl_add_u32 v4, v4, 9, v106
	v_lshl_add_u32 v5, v5, 9, v106
	v_lshl_add_u32 v6, v6, 9, v106
	v_lshl_add_u32 v7, v7, 9, v106
	v_lshl_add_u32 v8, v8, 9, v106
	v_lshl_add_u32 v9, v9, 9, v106
	v_lshl_add_u32 v10, v10, 9, v106
	v_lshl_add_u32 v11, v11, 9, v106
	v_lshl_add_u32 v12, v12, 9, v106
	v_lshl_add_u32 v13, v13, 9, v106
	v_lshl_add_u32 v14, v14, 9, v106
	v_lshl_add_u32 v15, v15, 9, v106
	s_waitcnt lgkmcnt(0)
	v_lshl_add_u32 v53, v53, 7, v54
	global_store_dword v254, v53, s[38:39] offset:36
	ds_read_b32 v0, v0 offset:32768
	ds_read_b32 v1, v1 offset:32768
	ds_read_b32 v2, v2 offset:32768
	ds_read_b32 v3, v3 offset:32768
	ds_read_b32 v4, v4 offset:32768
	ds_read_b32 v5, v5 offset:32768
	ds_read_b32 v6, v6 offset:32768
	ds_read_b32 v7, v7 offset:32768
	ds_read_b32 v8, v8 offset:32768
	ds_read_b32 v9, v9 offset:32768
	ds_read_b32 v10, v10 offset:32768
	ds_read_b32 v11, v11 offset:32768
	ds_read_b32 v12, v12 offset:32768
	ds_read_b32 v13, v13 offset:32768
	ds_read_b32 v14, v14 offset:32768
	ds_read_b32 v15, v15 offset:32768
	s_waitcnt lgkmcnt(0)
	v_add_f32_e32 v0, v32, v0
	v_add_f32_e32 v1, v33, v1
	v_add_f32_e32 v2, v34, v2
	v_add_f32_e32 v3, v35, v3
	v_add_f32_e32 v4, v36, v4
	v_add_f32_e32 v5, v37, v5
	v_add_f32_e32 v6, v38, v6
	v_add_f32_e32 v7, v39, v7
	v_add_f32_e32 v8, v40, v8
	v_add_f32_e32 v9, v41, v9
	v_add_f32_e32 v10, v42, v10
	v_add_f32_e32 v11, v43, v11
	v_add_f32_e32 v12, v44, v12
	v_add_f32_e32 v13, v45, v13
	v_add_f32_e32 v14, v46, v14
	v_add_f32_e32 v15, v47, v15
	v_cmp_gt_f32_e32 vcc, v1, v0
	v_cmp_gt_f32_e64 s[18:19], v3, v2
	v_cmp_gt_f32_e64 s[98:99], v5, v4
	v_cmp_gt_f32_e64 s[100:101], v7, v6
	v_cndmask_b32_e64 v0, v0, v1, vcc
	v_cndmask_b32_e64 v1, 0, 1, vcc
	v_cndmask_b32_e64 v2, v2, v3, s[18:19]
	v_cndmask_b32_e64 v3, 2, 3, s[18:19]
	v_cndmask_b32_e64 v4, v4, v5, s[98:99]
	v_cndmask_b32_e64 v5, 4, 5, s[98:99]
	v_cndmask_b32_e64 v6, v6, v7, s[100:101]
	v_cndmask_b32_e64 v7, 6, 7, s[100:101]
	v_cmp_gt_f32_e32 vcc, v9, v8
	v_cmp_gt_f32_e64 s[18:19], v11, v10
	v_cmp_gt_f32_e64 s[98:99], v13, v12
	v_cmp_gt_f32_e64 s[100:101], v15, v14
	v_cndmask_b32_e64 v8, v8, v9, vcc
	v_cndmask_b32_e64 v9, 8, 9, vcc
	v_cndmask_b32_e64 v10, v10, v11, s[18:19]
	v_cndmask_b32_e64 v11, 10, 11, s[18:19]
	v_cndmask_b32_e64 v12, v12, v13, s[98:99]
	v_cndmask_b32_e64 v13, 12, 13, s[98:99]
	v_cndmask_b32_e64 v14, v14, v15, s[100:101]
	v_cndmask_b32_e64 v15, 14, 15, s[100:101]
	v_cmp_gt_f32_e32 vcc, v2, v0
	v_cmp_gt_f32_e64 s[18:19], v6, v4
	v_cmp_gt_f32_e64 s[98:99], v10, v8
	v_cmp_gt_f32_e64 s[100:101], v14, v12
	v_cndmask_b32_e64 v0, v0, v2, vcc
	v_cndmask_b32_e64 v1, v1, v3, vcc
	v_cndmask_b32_e64 v4, v4, v6, s[18:19]
	v_cndmask_b32_e64 v5, v5, v7, s[18:19]
	v_cndmask_b32_e64 v8, v8, v10, s[98:99]
	v_cndmask_b32_e64 v9, v9, v11, s[98:99]
	v_cndmask_b32_e64 v12, v12, v14, s[100:101]
	v_cndmask_b32_e64 v13, v13, v15, s[100:101]
	v_cmp_gt_f32_e32 vcc, v4, v0
	v_cmp_gt_f32_e64 s[18:19], v12, v8
	s_nop 0
	v_cndmask_b32_e64 v0, v0, v4, vcc
	v_cndmask_b32_e64 v1, v1, v5, vcc
	v_cndmask_b32_e64 v8, v8, v12, s[18:19]
	v_cndmask_b32_e64 v9, v9, v13, s[18:19]
	v_cmp_gt_f32_e32 vcc, v8, v0
	s_nop 1
	v_cndmask_b32_e64 v0, v0, v8, vcc
	v_cndmask_b32_e64 v1, v1, v9, vcc
	v_sub_f32_e32 v26, v0, v255
	v_mul_f32_e32 v26, 0x3fb8aa3b, v26
	v_exp_f32_e32 v26, v26
	v_lshlrev_b32_e32 v50, 2, v1
	v_lshrrev_b64 v[52:53], v50, v[48:49]
	v_lshl_add_u32 v51, v1, 7, v107
	v_and_b32_e32 v52, 15, v52
	v_lshl_add_u32 v52, v52, 7, v206
	ds_read_u8 v53, v51
	ds_read_u8 v54, v52 offset:40960
	v_lshlrev_b64 v[50:51], v50, 1
	v_lshl_add_u64 v[48:49], v[50:51], 0, v[48:49]
	v_bfe_u32 v0, v48, 0, 4
	v_bfe_u32 v1, v48, 4, 4
	v_bfe_u32 v2, v48, 8, 4
	v_bfe_u32 v3, v48, 12, 4
	v_bfe_u32 v4, v48, 16, 4
	v_bfe_u32 v5, v48, 20, 4
	v_bfe_u32 v6, v48, 24, 4
	v_bfe_u32 v7, v48, 28, 4
	v_bfe_u32 v8, v49, 0, 4
	v_bfe_u32 v9, v49, 4, 4
	v_bfe_u32 v10, v49, 8, 4
	v_bfe_u32 v11, v49, 12, 4
	v_bfe_u32 v12, v49, 16, 4
	v_bfe_u32 v13, v49, 20, 4
	v_bfe_u32 v14, v49, 24, 4
	v_bfe_u32 v15, v49, 28, 4
	v_lshl_add_u32 v0, v0, 9, v106
	v_lshl_add_u32 v1, v1, 9, v106
	v_lshl_add_u32 v2, v2, 9, v106
	v_lshl_add_u32 v3, v3, 9, v106
	v_lshl_add_u32 v4, v4, 9, v106
	v_lshl_add_u32 v5, v5, 9, v106
	v_lshl_add_u32 v6, v6, 9, v106
	v_lshl_add_u32 v7, v7, 9, v106
	v_lshl_add_u32 v8, v8, 9, v106
	v_lshl_add_u32 v9, v9, 9, v106
	v_lshl_add_u32 v10, v10, 9, v106
	v_lshl_add_u32 v11, v11, 9, v106
	v_lshl_add_u32 v12, v12, 9, v106
	v_lshl_add_u32 v13, v13, 9, v106
	v_lshl_add_u32 v14, v14, 9, v106
	v_lshl_add_u32 v15, v15, 9, v106
	s_waitcnt lgkmcnt(0)
	v_lshl_add_u32 v53, v53, 7, v54
	global_store_dword v254, v53, s[38:39] offset:40
	ds_read_b32 v0, v0 offset:32768
	ds_read_b32 v1, v1 offset:32768
	ds_read_b32 v2, v2 offset:32768
	ds_read_b32 v3, v3 offset:32768
	ds_read_b32 v4, v4 offset:32768
	ds_read_b32 v5, v5 offset:32768
	ds_read_b32 v6, v6 offset:32768
	ds_read_b32 v7, v7 offset:32768
	ds_read_b32 v8, v8 offset:32768
	ds_read_b32 v9, v9 offset:32768
	ds_read_b32 v10, v10 offset:32768
	ds_read_b32 v11, v11 offset:32768
	ds_read_b32 v12, v12 offset:32768
	ds_read_b32 v13, v13 offset:32768
	ds_read_b32 v14, v14 offset:32768
	ds_read_b32 v15, v15 offset:32768
	s_waitcnt lgkmcnt(0)
	v_add_f32_e32 v0, v32, v0
	v_add_f32_e32 v1, v33, v1
	v_add_f32_e32 v2, v34, v2
	v_add_f32_e32 v3, v35, v3
	v_add_f32_e32 v4, v36, v4
	v_add_f32_e32 v5, v37, v5
	v_add_f32_e32 v6, v38, v6
	v_add_f32_e32 v7, v39, v7
	v_add_f32_e32 v8, v40, v8
	v_add_f32_e32 v9, v41, v9
	v_add_f32_e32 v10, v42, v10
	v_add_f32_e32 v11, v43, v11
	v_add_f32_e32 v12, v44, v12
	v_add_f32_e32 v13, v45, v13
	v_add_f32_e32 v14, v46, v14
	v_add_f32_e32 v15, v47, v15
	v_cmp_gt_f32_e32 vcc, v1, v0
	v_cmp_gt_f32_e64 s[18:19], v3, v2
	v_cmp_gt_f32_e64 s[98:99], v5, v4
	v_cmp_gt_f32_e64 s[100:101], v7, v6
	v_cndmask_b32_e64 v0, v0, v1, vcc
	v_cndmask_b32_e64 v1, 0, 1, vcc
	v_cndmask_b32_e64 v2, v2, v3, s[18:19]
	v_cndmask_b32_e64 v3, 2, 3, s[18:19]
	v_cndmask_b32_e64 v4, v4, v5, s[98:99]
	v_cndmask_b32_e64 v5, 4, 5, s[98:99]
	v_cndmask_b32_e64 v6, v6, v7, s[100:101]
	v_cndmask_b32_e64 v7, 6, 7, s[100:101]
	v_cmp_gt_f32_e32 vcc, v9, v8
	v_cmp_gt_f32_e64 s[18:19], v11, v10
	v_cmp_gt_f32_e64 s[98:99], v13, v12
	v_cmp_gt_f32_e64 s[100:101], v15, v14
	v_cndmask_b32_e64 v8, v8, v9, vcc
	v_cndmask_b32_e64 v9, 8, 9, vcc
	v_cndmask_b32_e64 v10, v10, v11, s[18:19]
	v_cndmask_b32_e64 v11, 10, 11, s[18:19]
	v_cndmask_b32_e64 v12, v12, v13, s[98:99]
	v_cndmask_b32_e64 v13, 12, 13, s[98:99]
	v_cndmask_b32_e64 v14, v14, v15, s[100:101]
	v_cndmask_b32_e64 v15, 14, 15, s[100:101]
	v_cmp_gt_f32_e32 vcc, v2, v0
	v_cmp_gt_f32_e64 s[18:19], v6, v4
	v_cmp_gt_f32_e64 s[98:99], v10, v8
	v_cmp_gt_f32_e64 s[100:101], v14, v12
	v_cndmask_b32_e64 v0, v0, v2, vcc
	v_cndmask_b32_e64 v1, v1, v3, vcc
	v_cndmask_b32_e64 v4, v4, v6, s[18:19]
	v_cndmask_b32_e64 v5, v5, v7, s[18:19]
	v_cndmask_b32_e64 v8, v8, v10, s[98:99]
	v_cndmask_b32_e64 v9, v9, v11, s[98:99]
	v_cndmask_b32_e64 v12, v12, v14, s[100:101]
	v_cndmask_b32_e64 v13, v13, v15, s[100:101]
	v_cmp_gt_f32_e32 vcc, v4, v0
	v_cmp_gt_f32_e64 s[18:19], v12, v8
	s_nop 0
	v_cndmask_b32_e64 v0, v0, v4, vcc
	v_cndmask_b32_e64 v1, v1, v5, vcc
	v_cndmask_b32_e64 v8, v8, v12, s[18:19]
	v_cndmask_b32_e64 v9, v9, v13, s[18:19]
	v_cmp_gt_f32_e32 vcc, v8, v0
	s_nop 1
	v_cndmask_b32_e64 v0, v0, v8, vcc
	v_cndmask_b32_e64 v1, v1, v9, vcc
	v_sub_f32_e32 v27, v0, v255
	v_mul_f32_e32 v27, 0x3fb8aa3b, v27
	v_exp_f32_e32 v27, v27
	v_lshlrev_b32_e32 v50, 2, v1
	v_lshrrev_b64 v[52:53], v50, v[48:49]
	v_lshl_add_u32 v51, v1, 7, v107
	v_and_b32_e32 v52, 15, v52
	v_lshl_add_u32 v52, v52, 7, v206
	ds_read_u8 v53, v51
	ds_read_u8 v54, v52 offset:40960
	v_lshlrev_b64 v[50:51], v50, 1
	v_lshl_add_u64 v[48:49], v[50:51], 0, v[48:49]
	v_bfe_u32 v0, v48, 0, 4
	v_bfe_u32 v1, v48, 4, 4
	v_bfe_u32 v2, v48, 8, 4
	v_bfe_u32 v3, v48, 12, 4
	v_bfe_u32 v4, v48, 16, 4
	v_bfe_u32 v5, v48, 20, 4
	v_bfe_u32 v6, v48, 24, 4
	v_bfe_u32 v7, v48, 28, 4
	v_bfe_u32 v8, v49, 0, 4
	v_bfe_u32 v9, v49, 4, 4
	v_bfe_u32 v10, v49, 8, 4
	v_bfe_u32 v11, v49, 12, 4
	v_bfe_u32 v12, v49, 16, 4
	v_bfe_u32 v13, v49, 20, 4
	v_bfe_u32 v14, v49, 24, 4
	v_bfe_u32 v15, v49, 28, 4
	v_lshl_add_u32 v0, v0, 9, v106
	v_lshl_add_u32 v1, v1, 9, v106
	v_lshl_add_u32 v2, v2, 9, v106
	v_lshl_add_u32 v3, v3, 9, v106
	v_lshl_add_u32 v4, v4, 9, v106
	v_lshl_add_u32 v5, v5, 9, v106
	v_lshl_add_u32 v6, v6, 9, v106
	v_lshl_add_u32 v7, v7, 9, v106
	v_lshl_add_u32 v8, v8, 9, v106
	v_lshl_add_u32 v9, v9, 9, v106
	v_lshl_add_u32 v10, v10, 9, v106
	v_lshl_add_u32 v11, v11, 9, v106
	v_lshl_add_u32 v12, v12, 9, v106
	v_lshl_add_u32 v13, v13, 9, v106
	v_lshl_add_u32 v14, v14, 9, v106
	v_lshl_add_u32 v15, v15, 9, v106
	s_waitcnt lgkmcnt(0)
	v_lshl_add_u32 v53, v53, 7, v54
	global_store_dword v254, v53, s[38:39] offset:44
	ds_read_b32 v0, v0 offset:32768
	ds_read_b32 v1, v1 offset:32768
	ds_read_b32 v2, v2 offset:32768
	ds_read_b32 v3, v3 offset:32768
	ds_read_b32 v4, v4 offset:32768
	ds_read_b32 v5, v5 offset:32768
	ds_read_b32 v6, v6 offset:32768
	ds_read_b32 v7, v7 offset:32768
	ds_read_b32 v8, v8 offset:32768
	ds_read_b32 v9, v9 offset:32768
	ds_read_b32 v10, v10 offset:32768
	ds_read_b32 v11, v11 offset:32768
	ds_read_b32 v12, v12 offset:32768
	ds_read_b32 v13, v13 offset:32768
	ds_read_b32 v14, v14 offset:32768
	ds_read_b32 v15, v15 offset:32768
	s_waitcnt lgkmcnt(0)
	v_add_f32_e32 v0, v32, v0
	v_add_f32_e32 v1, v33, v1
	v_add_f32_e32 v2, v34, v2
	v_add_f32_e32 v3, v35, v3
	v_add_f32_e32 v4, v36, v4
	v_add_f32_e32 v5, v37, v5
	v_add_f32_e32 v6, v38, v6
	v_add_f32_e32 v7, v39, v7
	v_add_f32_e32 v8, v40, v8
	v_add_f32_e32 v9, v41, v9
	v_add_f32_e32 v10, v42, v10
	v_add_f32_e32 v11, v43, v11
	v_add_f32_e32 v12, v44, v12
	v_add_f32_e32 v13, v45, v13
	v_add_f32_e32 v14, v46, v14
	v_add_f32_e32 v15, v47, v15
	v_cmp_gt_f32_e32 vcc, v1, v0
	v_cmp_gt_f32_e64 s[18:19], v3, v2
	v_cmp_gt_f32_e64 s[98:99], v5, v4
	v_cmp_gt_f32_e64 s[100:101], v7, v6
	v_cndmask_b32_e64 v0, v0, v1, vcc
	v_cndmask_b32_e64 v1, 0, 1, vcc
	v_cndmask_b32_e64 v2, v2, v3, s[18:19]
	v_cndmask_b32_e64 v3, 2, 3, s[18:19]
	v_cndmask_b32_e64 v4, v4, v5, s[98:99]
	v_cndmask_b32_e64 v5, 4, 5, s[98:99]
	v_cndmask_b32_e64 v6, v6, v7, s[100:101]
	v_cndmask_b32_e64 v7, 6, 7, s[100:101]
	v_cmp_gt_f32_e32 vcc, v9, v8
	v_cmp_gt_f32_e64 s[18:19], v11, v10
	v_cmp_gt_f32_e64 s[98:99], v13, v12
	v_cmp_gt_f32_e64 s[100:101], v15, v14
	v_cndmask_b32_e64 v8, v8, v9, vcc
	v_cndmask_b32_e64 v9, 8, 9, vcc
	v_cndmask_b32_e64 v10, v10, v11, s[18:19]
	v_cndmask_b32_e64 v11, 10, 11, s[18:19]
	v_cndmask_b32_e64 v12, v12, v13, s[98:99]
	v_cndmask_b32_e64 v13, 12, 13, s[98:99]
	v_cndmask_b32_e64 v14, v14, v15, s[100:101]
	v_cndmask_b32_e64 v15, 14, 15, s[100:101]
	v_cmp_gt_f32_e32 vcc, v2, v0
	v_cmp_gt_f32_e64 s[18:19], v6, v4
	v_cmp_gt_f32_e64 s[98:99], v10, v8
	v_cmp_gt_f32_e64 s[100:101], v14, v12
	v_cndmask_b32_e64 v0, v0, v2, vcc
	v_cndmask_b32_e64 v1, v1, v3, vcc
	v_cndmask_b32_e64 v4, v4, v6, s[18:19]
	v_cndmask_b32_e64 v5, v5, v7, s[18:19]
	v_cndmask_b32_e64 v8, v8, v10, s[98:99]
	v_cndmask_b32_e64 v9, v9, v11, s[98:99]
	v_cndmask_b32_e64 v12, v12, v14, s[100:101]
	v_cndmask_b32_e64 v13, v13, v15, s[100:101]
	v_cmp_gt_f32_e32 vcc, v4, v0
	v_cmp_gt_f32_e64 s[18:19], v12, v8
	s_nop 0
	v_cndmask_b32_e64 v0, v0, v4, vcc
	v_cndmask_b32_e64 v1, v1, v5, vcc
	v_cndmask_b32_e64 v8, v8, v12, s[18:19]
	v_cndmask_b32_e64 v9, v9, v13, s[18:19]
	v_cmp_gt_f32_e32 vcc, v8, v0
	s_nop 1
	v_cndmask_b32_e64 v0, v0, v8, vcc
	v_cndmask_b32_e64 v1, v1, v9, vcc
	v_sub_f32_e32 v28, v0, v255
	v_mul_f32_e32 v28, 0x3fb8aa3b, v28
	v_exp_f32_e32 v28, v28
	v_lshlrev_b32_e32 v50, 2, v1
	v_lshrrev_b64 v[52:53], v50, v[48:49]
	v_lshl_add_u32 v51, v1, 7, v107
	v_and_b32_e32 v52, 15, v52
	v_lshl_add_u32 v52, v52, 7, v206
	ds_read_u8 v53, v51
	ds_read_u8 v54, v52 offset:40960
	v_lshlrev_b64 v[50:51], v50, 1
	v_lshl_add_u64 v[48:49], v[50:51], 0, v[48:49]
	v_bfe_u32 v0, v48, 0, 4
	v_bfe_u32 v1, v48, 4, 4
	v_bfe_u32 v2, v48, 8, 4
	v_bfe_u32 v3, v48, 12, 4
	v_bfe_u32 v4, v48, 16, 4
	v_bfe_u32 v5, v48, 20, 4
	v_bfe_u32 v6, v48, 24, 4
	v_bfe_u32 v7, v48, 28, 4
	v_bfe_u32 v8, v49, 0, 4
	v_bfe_u32 v9, v49, 4, 4
	v_bfe_u32 v10, v49, 8, 4
	v_bfe_u32 v11, v49, 12, 4
	v_bfe_u32 v12, v49, 16, 4
	v_bfe_u32 v13, v49, 20, 4
	v_bfe_u32 v14, v49, 24, 4
	v_bfe_u32 v15, v49, 28, 4
	v_lshl_add_u32 v0, v0, 9, v106
	v_lshl_add_u32 v1, v1, 9, v106
	v_lshl_add_u32 v2, v2, 9, v106
	v_lshl_add_u32 v3, v3, 9, v106
	v_lshl_add_u32 v4, v4, 9, v106
	v_lshl_add_u32 v5, v5, 9, v106
	v_lshl_add_u32 v6, v6, 9, v106
	v_lshl_add_u32 v7, v7, 9, v106
	v_lshl_add_u32 v8, v8, 9, v106
	v_lshl_add_u32 v9, v9, 9, v106
	v_lshl_add_u32 v10, v10, 9, v106
	v_lshl_add_u32 v11, v11, 9, v106
	v_lshl_add_u32 v12, v12, 9, v106
	v_lshl_add_u32 v13, v13, 9, v106
	v_lshl_add_u32 v14, v14, 9, v106
	v_lshl_add_u32 v15, v15, 9, v106
	s_waitcnt lgkmcnt(0)
	v_lshl_add_u32 v53, v53, 7, v54
	global_store_dword v254, v53, s[38:39] offset:48
	ds_read_b32 v0, v0 offset:32768
	ds_read_b32 v1, v1 offset:32768
	ds_read_b32 v2, v2 offset:32768
	ds_read_b32 v3, v3 offset:32768
	ds_read_b32 v4, v4 offset:32768
	ds_read_b32 v5, v5 offset:32768
	ds_read_b32 v6, v6 offset:32768
	ds_read_b32 v7, v7 offset:32768
	ds_read_b32 v8, v8 offset:32768
	ds_read_b32 v9, v9 offset:32768
	ds_read_b32 v10, v10 offset:32768
	ds_read_b32 v11, v11 offset:32768
	ds_read_b32 v12, v12 offset:32768
	ds_read_b32 v13, v13 offset:32768
	ds_read_b32 v14, v14 offset:32768
	ds_read_b32 v15, v15 offset:32768
	s_waitcnt lgkmcnt(0)
	v_add_f32_e32 v0, v32, v0
	v_add_f32_e32 v1, v33, v1
	v_add_f32_e32 v2, v34, v2
	v_add_f32_e32 v3, v35, v3
	v_add_f32_e32 v4, v36, v4
	v_add_f32_e32 v5, v37, v5
	v_add_f32_e32 v6, v38, v6
	v_add_f32_e32 v7, v39, v7
	v_add_f32_e32 v8, v40, v8
	v_add_f32_e32 v9, v41, v9
	v_add_f32_e32 v10, v42, v10
	v_add_f32_e32 v11, v43, v11
	v_add_f32_e32 v12, v44, v12
	v_add_f32_e32 v13, v45, v13
	v_add_f32_e32 v14, v46, v14
	v_add_f32_e32 v15, v47, v15
	v_cmp_gt_f32_e32 vcc, v1, v0
	v_cmp_gt_f32_e64 s[18:19], v3, v2
	v_cmp_gt_f32_e64 s[98:99], v5, v4
	v_cmp_gt_f32_e64 s[100:101], v7, v6
	v_cndmask_b32_e64 v0, v0, v1, vcc
	v_cndmask_b32_e64 v1, 0, 1, vcc
	v_cndmask_b32_e64 v2, v2, v3, s[18:19]
	v_cndmask_b32_e64 v3, 2, 3, s[18:19]
	v_cndmask_b32_e64 v4, v4, v5, s[98:99]
	v_cndmask_b32_e64 v5, 4, 5, s[98:99]
	v_cndmask_b32_e64 v6, v6, v7, s[100:101]
	v_cndmask_b32_e64 v7, 6, 7, s[100:101]
	v_cmp_gt_f32_e32 vcc, v9, v8
	v_cmp_gt_f32_e64 s[18:19], v11, v10
	v_cmp_gt_f32_e64 s[98:99], v13, v12
	v_cmp_gt_f32_e64 s[100:101], v15, v14
	v_cndmask_b32_e64 v8, v8, v9, vcc
	v_cndmask_b32_e64 v9, 8, 9, vcc
	v_cndmask_b32_e64 v10, v10, v11, s[18:19]
	v_cndmask_b32_e64 v11, 10, 11, s[18:19]
	v_cndmask_b32_e64 v12, v12, v13, s[98:99]
	v_cndmask_b32_e64 v13, 12, 13, s[98:99]
	v_cndmask_b32_e64 v14, v14, v15, s[100:101]
	v_cndmask_b32_e64 v15, 14, 15, s[100:101]
	v_cmp_gt_f32_e32 vcc, v2, v0
	v_cmp_gt_f32_e64 s[18:19], v6, v4
	v_cmp_gt_f32_e64 s[98:99], v10, v8
	v_cmp_gt_f32_e64 s[100:101], v14, v12
	v_cndmask_b32_e64 v0, v0, v2, vcc
	v_cndmask_b32_e64 v1, v1, v3, vcc
	v_cndmask_b32_e64 v4, v4, v6, s[18:19]
	v_cndmask_b32_e64 v5, v5, v7, s[18:19]
	v_cndmask_b32_e64 v8, v8, v10, s[98:99]
	v_cndmask_b32_e64 v9, v9, v11, s[98:99]
	v_cndmask_b32_e64 v12, v12, v14, s[100:101]
	v_cndmask_b32_e64 v13, v13, v15, s[100:101]
	v_cmp_gt_f32_e32 vcc, v4, v0
	v_cmp_gt_f32_e64 s[18:19], v12, v8
	s_nop 0
	v_cndmask_b32_e64 v0, v0, v4, vcc
	v_cndmask_b32_e64 v1, v1, v5, vcc
	v_cndmask_b32_e64 v8, v8, v12, s[18:19]
	v_cndmask_b32_e64 v9, v9, v13, s[18:19]
	v_cmp_gt_f32_e32 vcc, v8, v0
	s_nop 1
	v_cndmask_b32_e64 v0, v0, v8, vcc
	v_cndmask_b32_e64 v1, v1, v9, vcc
	v_sub_f32_e32 v29, v0, v255
	v_mul_f32_e32 v29, 0x3fb8aa3b, v29
	v_exp_f32_e32 v29, v29
	v_lshlrev_b32_e32 v50, 2, v1
	v_lshrrev_b64 v[52:53], v50, v[48:49]
	v_lshl_add_u32 v51, v1, 7, v107
	v_and_b32_e32 v52, 15, v52
	v_lshl_add_u32 v52, v52, 7, v206
	ds_read_u8 v53, v51
	ds_read_u8 v54, v52 offset:40960
	v_lshlrev_b64 v[50:51], v50, 1
	v_lshl_add_u64 v[48:49], v[50:51], 0, v[48:49]
	v_bfe_u32 v0, v48, 0, 4
	v_bfe_u32 v1, v48, 4, 4
	v_bfe_u32 v2, v48, 8, 4
	v_bfe_u32 v3, v48, 12, 4
	v_bfe_u32 v4, v48, 16, 4
	v_bfe_u32 v5, v48, 20, 4
	v_bfe_u32 v6, v48, 24, 4
	v_bfe_u32 v7, v48, 28, 4
	v_bfe_u32 v8, v49, 0, 4
	v_bfe_u32 v9, v49, 4, 4
	v_bfe_u32 v10, v49, 8, 4
	v_bfe_u32 v11, v49, 12, 4
	v_bfe_u32 v12, v49, 16, 4
	v_bfe_u32 v13, v49, 20, 4
	v_bfe_u32 v14, v49, 24, 4
	v_bfe_u32 v15, v49, 28, 4
	v_lshl_add_u32 v0, v0, 9, v106
	v_lshl_add_u32 v1, v1, 9, v106
	v_lshl_add_u32 v2, v2, 9, v106
	v_lshl_add_u32 v3, v3, 9, v106
	v_lshl_add_u32 v4, v4, 9, v106
	v_lshl_add_u32 v5, v5, 9, v106
	v_lshl_add_u32 v6, v6, 9, v106
	v_lshl_add_u32 v7, v7, 9, v106
	v_lshl_add_u32 v8, v8, 9, v106
	v_lshl_add_u32 v9, v9, 9, v106
	v_lshl_add_u32 v10, v10, 9, v106
	v_lshl_add_u32 v11, v11, 9, v106
	v_lshl_add_u32 v12, v12, 9, v106
	v_lshl_add_u32 v13, v13, 9, v106
	v_lshl_add_u32 v14, v14, 9, v106
	v_lshl_add_u32 v15, v15, 9, v106
	s_waitcnt lgkmcnt(0)
	v_lshl_add_u32 v53, v53, 7, v54
	global_store_dword v254, v53, s[38:39] offset:52
	ds_read_b32 v0, v0 offset:32768
	ds_read_b32 v1, v1 offset:32768
	ds_read_b32 v2, v2 offset:32768
	ds_read_b32 v3, v3 offset:32768
	ds_read_b32 v4, v4 offset:32768
	ds_read_b32 v5, v5 offset:32768
	ds_read_b32 v6, v6 offset:32768
	ds_read_b32 v7, v7 offset:32768
	ds_read_b32 v8, v8 offset:32768
	ds_read_b32 v9, v9 offset:32768
	ds_read_b32 v10, v10 offset:32768
	ds_read_b32 v11, v11 offset:32768
	ds_read_b32 v12, v12 offset:32768
	ds_read_b32 v13, v13 offset:32768
	ds_read_b32 v14, v14 offset:32768
	ds_read_b32 v15, v15 offset:32768
	s_waitcnt lgkmcnt(0)
	v_add_f32_e32 v0, v32, v0
	v_add_f32_e32 v1, v33, v1
	v_add_f32_e32 v2, v34, v2
	v_add_f32_e32 v3, v35, v3
	v_add_f32_e32 v4, v36, v4
	v_add_f32_e32 v5, v37, v5
	v_add_f32_e32 v6, v38, v6
	v_add_f32_e32 v7, v39, v7
	v_add_f32_e32 v8, v40, v8
	v_add_f32_e32 v9, v41, v9
	v_add_f32_e32 v10, v42, v10
	v_add_f32_e32 v11, v43, v11
	v_add_f32_e32 v12, v44, v12
	v_add_f32_e32 v13, v45, v13
	v_add_f32_e32 v14, v46, v14
	v_add_f32_e32 v15, v47, v15
	v_cmp_gt_f32_e32 vcc, v1, v0
	v_cmp_gt_f32_e64 s[18:19], v3, v2
	v_cmp_gt_f32_e64 s[98:99], v5, v4
	v_cmp_gt_f32_e64 s[100:101], v7, v6
	v_cndmask_b32_e64 v0, v0, v1, vcc
	v_cndmask_b32_e64 v1, 0, 1, vcc
	v_cndmask_b32_e64 v2, v2, v3, s[18:19]
	v_cndmask_b32_e64 v3, 2, 3, s[18:19]
	v_cndmask_b32_e64 v4, v4, v5, s[98:99]
	v_cndmask_b32_e64 v5, 4, 5, s[98:99]
	v_cndmask_b32_e64 v6, v6, v7, s[100:101]
	v_cndmask_b32_e64 v7, 6, 7, s[100:101]
	v_cmp_gt_f32_e32 vcc, v9, v8
	v_cmp_gt_f32_e64 s[18:19], v11, v10
	v_cmp_gt_f32_e64 s[98:99], v13, v12
	v_cmp_gt_f32_e64 s[100:101], v15, v14
	v_cndmask_b32_e64 v8, v8, v9, vcc
	v_cndmask_b32_e64 v9, 8, 9, vcc
	v_cndmask_b32_e64 v10, v10, v11, s[18:19]
	v_cndmask_b32_e64 v11, 10, 11, s[18:19]
	v_cndmask_b32_e64 v12, v12, v13, s[98:99]
	v_cndmask_b32_e64 v13, 12, 13, s[98:99]
	v_cndmask_b32_e64 v14, v14, v15, s[100:101]
	v_cndmask_b32_e64 v15, 14, 15, s[100:101]
	v_cmp_gt_f32_e32 vcc, v2, v0
	v_cmp_gt_f32_e64 s[18:19], v6, v4
	v_cmp_gt_f32_e64 s[98:99], v10, v8
	v_cmp_gt_f32_e64 s[100:101], v14, v12
	v_cndmask_b32_e64 v0, v0, v2, vcc
	v_cndmask_b32_e64 v1, v1, v3, vcc
	v_cndmask_b32_e64 v4, v4, v6, s[18:19]
	v_cndmask_b32_e64 v5, v5, v7, s[18:19]
	v_cndmask_b32_e64 v8, v8, v10, s[98:99]
	v_cndmask_b32_e64 v9, v9, v11, s[98:99]
	v_cndmask_b32_e64 v12, v12, v14, s[100:101]
	v_cndmask_b32_e64 v13, v13, v15, s[100:101]
	v_cmp_gt_f32_e32 vcc, v4, v0
	v_cmp_gt_f32_e64 s[18:19], v12, v8
	s_nop 0
	v_cndmask_b32_e64 v0, v0, v4, vcc
	v_cndmask_b32_e64 v1, v1, v5, vcc
	v_cndmask_b32_e64 v8, v8, v12, s[18:19]
	v_cndmask_b32_e64 v9, v9, v13, s[18:19]
	v_cmp_gt_f32_e32 vcc, v8, v0
	s_nop 1
	v_cndmask_b32_e64 v0, v0, v8, vcc
	v_cndmask_b32_e64 v1, v1, v9, vcc
	v_sub_f32_e32 v30, v0, v255
	v_mul_f32_e32 v30, 0x3fb8aa3b, v30
	v_exp_f32_e32 v30, v30
	v_lshlrev_b32_e32 v50, 2, v1
	v_lshrrev_b64 v[52:53], v50, v[48:49]
	v_lshl_add_u32 v51, v1, 7, v107
	v_and_b32_e32 v52, 15, v52
	v_lshl_add_u32 v52, v52, 7, v206
	ds_read_u8 v53, v51
	ds_read_u8 v54, v52 offset:40960
	v_lshlrev_b64 v[50:51], v50, 1
	v_lshl_add_u64 v[48:49], v[50:51], 0, v[48:49]
	v_bfe_u32 v0, v48, 0, 4
	v_bfe_u32 v1, v48, 4, 4
	v_bfe_u32 v2, v48, 8, 4
	v_bfe_u32 v3, v48, 12, 4
	v_bfe_u32 v4, v48, 16, 4
	v_bfe_u32 v5, v48, 20, 4
	v_bfe_u32 v6, v48, 24, 4
	v_bfe_u32 v7, v48, 28, 4
	v_bfe_u32 v8, v49, 0, 4
	v_bfe_u32 v9, v49, 4, 4
	v_bfe_u32 v10, v49, 8, 4
	v_bfe_u32 v11, v49, 12, 4
	v_bfe_u32 v12, v49, 16, 4
	v_bfe_u32 v13, v49, 20, 4
	v_bfe_u32 v14, v49, 24, 4
	v_bfe_u32 v15, v49, 28, 4
	v_lshl_add_u32 v0, v0, 9, v106
	v_lshl_add_u32 v1, v1, 9, v106
	v_lshl_add_u32 v2, v2, 9, v106
	v_lshl_add_u32 v3, v3, 9, v106
	v_lshl_add_u32 v4, v4, 9, v106
	v_lshl_add_u32 v5, v5, 9, v106
	v_lshl_add_u32 v6, v6, 9, v106
	v_lshl_add_u32 v7, v7, 9, v106
	v_lshl_add_u32 v8, v8, 9, v106
	v_lshl_add_u32 v9, v9, 9, v106
	v_lshl_add_u32 v10, v10, 9, v106
	v_lshl_add_u32 v11, v11, 9, v106
	v_lshl_add_u32 v12, v12, 9, v106
	v_lshl_add_u32 v13, v13, 9, v106
	v_lshl_add_u32 v14, v14, 9, v106
	v_lshl_add_u32 v15, v15, 9, v106
	s_waitcnt lgkmcnt(0)
	v_lshl_add_u32 v53, v53, 7, v54
	global_store_dword v254, v53, s[38:39] offset:56
	ds_read_b32 v0, v0 offset:32768
	ds_read_b32 v1, v1 offset:32768
	ds_read_b32 v2, v2 offset:32768
	ds_read_b32 v3, v3 offset:32768
	ds_read_b32 v4, v4 offset:32768
	ds_read_b32 v5, v5 offset:32768
	ds_read_b32 v6, v6 offset:32768
	ds_read_b32 v7, v7 offset:32768
	ds_read_b32 v8, v8 offset:32768
	ds_read_b32 v9, v9 offset:32768
	ds_read_b32 v10, v10 offset:32768
	ds_read_b32 v11, v11 offset:32768
	ds_read_b32 v12, v12 offset:32768
	ds_read_b32 v13, v13 offset:32768
	ds_read_b32 v14, v14 offset:32768
	ds_read_b32 v15, v15 offset:32768
	s_waitcnt lgkmcnt(0)
	v_add_f32_e32 v0, v32, v0
	v_add_f32_e32 v1, v33, v1
	v_add_f32_e32 v2, v34, v2
	v_add_f32_e32 v3, v35, v3
	v_add_f32_e32 v4, v36, v4
	v_add_f32_e32 v5, v37, v5
	v_add_f32_e32 v6, v38, v6
	v_add_f32_e32 v7, v39, v7
	v_add_f32_e32 v8, v40, v8
	v_add_f32_e32 v9, v41, v9
	v_add_f32_e32 v10, v42, v10
	v_add_f32_e32 v11, v43, v11
	v_add_f32_e32 v12, v44, v12
	v_add_f32_e32 v13, v45, v13
	v_add_f32_e32 v14, v46, v14
	v_add_f32_e32 v15, v47, v15
	v_cmp_gt_f32_e32 vcc, v1, v0
	v_cmp_gt_f32_e64 s[18:19], v3, v2
	v_cmp_gt_f32_e64 s[98:99], v5, v4
	v_cmp_gt_f32_e64 s[100:101], v7, v6
	v_cndmask_b32_e64 v0, v0, v1, vcc
	v_cndmask_b32_e64 v1, 0, 1, vcc
	v_cndmask_b32_e64 v2, v2, v3, s[18:19]
	v_cndmask_b32_e64 v3, 2, 3, s[18:19]
	v_cndmask_b32_e64 v4, v4, v5, s[98:99]
	v_cndmask_b32_e64 v5, 4, 5, s[98:99]
	v_cndmask_b32_e64 v6, v6, v7, s[100:101]
	v_cndmask_b32_e64 v7, 6, 7, s[100:101]
	v_cmp_gt_f32_e32 vcc, v9, v8
	v_cmp_gt_f32_e64 s[18:19], v11, v10
	v_cmp_gt_f32_e64 s[98:99], v13, v12
	v_cmp_gt_f32_e64 s[100:101], v15, v14
	v_cndmask_b32_e64 v8, v8, v9, vcc
	v_cndmask_b32_e64 v9, 8, 9, vcc
	v_cndmask_b32_e64 v10, v10, v11, s[18:19]
	v_cndmask_b32_e64 v11, 10, 11, s[18:19]
	v_cndmask_b32_e64 v12, v12, v13, s[98:99]
	v_cndmask_b32_e64 v13, 12, 13, s[98:99]
	v_cndmask_b32_e64 v14, v14, v15, s[100:101]
	v_cndmask_b32_e64 v15, 14, 15, s[100:101]
	v_cmp_gt_f32_e32 vcc, v2, v0
	v_cmp_gt_f32_e64 s[18:19], v6, v4
	v_cmp_gt_f32_e64 s[98:99], v10, v8
	v_cmp_gt_f32_e64 s[100:101], v14, v12
	v_cndmask_b32_e64 v0, v0, v2, vcc
	v_cndmask_b32_e64 v1, v1, v3, vcc
	v_cndmask_b32_e64 v4, v4, v6, s[18:19]
	v_cndmask_b32_e64 v5, v5, v7, s[18:19]
	v_cndmask_b32_e64 v8, v8, v10, s[98:99]
	v_cndmask_b32_e64 v9, v9, v11, s[98:99]
	v_cndmask_b32_e64 v12, v12, v14, s[100:101]
	v_cndmask_b32_e64 v13, v13, v15, s[100:101]
	v_cmp_gt_f32_e32 vcc, v4, v0
	v_cmp_gt_f32_e64 s[18:19], v12, v8
	s_nop 0
	v_cndmask_b32_e64 v0, v0, v4, vcc
	v_cndmask_b32_e64 v1, v1, v5, vcc
	v_cndmask_b32_e64 v8, v8, v12, s[18:19]
	v_cndmask_b32_e64 v9, v9, v13, s[18:19]
	v_cmp_gt_f32_e32 vcc, v8, v0
	s_nop 1
	v_cndmask_b32_e64 v0, v0, v8, vcc
	v_cndmask_b32_e64 v1, v1, v9, vcc
	v_sub_f32_e32 v31, v0, v255
	v_mul_f32_e32 v31, 0x3fb8aa3b, v31
	v_exp_f32_e32 v31, v31
	v_lshlrev_b32_e32 v50, 2, v1
	v_lshrrev_b64 v[52:53], v50, v[48:49]
	v_lshl_add_u32 v51, v1, 7, v107
	v_and_b32_e32 v52, 15, v52
	v_lshl_add_u32 v52, v52, 7, v206
	ds_read_u8 v53, v51
	ds_read_u8 v54, v52 offset:40960
	v_lshlrev_b64 v[50:51], v50, 1
	v_lshl_add_u64 v[48:49], v[50:51], 0, v[48:49]
	s_waitcnt lgkmcnt(0)
	v_lshl_add_u32 v53, v53, 7, v54
	global_store_dword v254, v53, s[38:39] offset:60
	v_add_f32_e32 v32, 0, v16
	v_add_f32_e32 v32, v32, v17
	v_add_f32_e32 v32, v32, v18
	v_add_f32_e32 v32, v32, v19
	v_add_f32_e32 v32, v32, v20
	v_add_f32_e32 v32, v32, v21
	v_add_f32_e32 v32, v32, v22
	v_add_f32_e32 v32, v32, v23
	v_add_f32_e32 v32, v32, v24
	v_add_f32_e32 v32, v32, v25
	v_add_f32_e32 v32, v32, v26
	v_add_f32_e32 v32, v32, v27
	v_add_f32_e32 v32, v32, v28
	v_add_f32_e32 v32, v32, v29
	v_add_f32_e32 v32, v32, v30
	v_add_f32_e32 v32, v32, v31
	v_div_scale_f32 v33, s[18:19], v32, v32, 1.0
	v_rcp_f32_e32 v34, v33
	s_nop 0
	v_fma_f32 v35, -v33, v34, 1.0
	v_fmac_f32_e32 v34, v35, v34
	v_div_scale_f32 v35, vcc, 1.0, v32, 1.0
	v_mul_f32_e32 v36, v35, v34
	v_fma_f32 v37, -v33, v36, v35
	v_fmac_f32_e32 v36, v37, v34
	v_fma_f32 v33, -v33, v36, v35
	s_nop 1
	v_div_fmas_f32 v33, v33, v34, v36
	v_div_fixup_f32 v32, v33, v32, 1.0
	v_mul_f32_e32 v16, v16, v32
	v_mul_f32_e32 v17, v17, v32
	v_mul_f32_e32 v18, v18, v32
	v_mul_f32_e32 v19, v19, v32
	v_mul_f32_e32 v20, v20, v32
	v_mul_f32_e32 v21, v21, v32
	v_mul_f32_e32 v22, v22, v32
	v_mul_f32_e32 v23, v23, v32
	v_mul_f32_e32 v24, v24, v32
	v_mul_f32_e32 v25, v25, v32
	v_mul_f32_e32 v26, v26, v32
	v_mul_f32_e32 v27, v27, v32
	v_mul_f32_e32 v28, v28, v32
	v_mul_f32_e32 v29, v29, v32
	v_mul_f32_e32 v30, v30, v32
	v_mul_f32_e32 v31, v31, v32
	global_store_dwordx4 v254, v[16:19], s[36:37] offset:0
	global_store_dwordx4 v254, v[20:23], s[36:37] offset:16
	global_store_dwordx4 v254, v[24:27], s[36:37] offset:32
	global_store_dwordx4 v254, v[28:31], s[36:37] offset:48
	s_branch .LBB0_1081
